# v14: hand-written in-proj epilogue (plain/sigmoid/silu variants, strided row addresses) + peeled first K-iteration with relaxed vmcnt so epilogue stores drain under the next unit's first phases; FB/ml
# speedup vs baseline: 1.0525x; 1.0086x over previous
.LBB0_258:
	s_and_b64 s[26:27], s[56:57], exec
	s_cselect_b32 s6, s53, s11
	s_cselect_b32 s36, s52, s10
	s_cselect_b32 s37, s55, s15
	s_cselect_b32 s40, s54, s14
	s_add_u32 s10, s10, 0x40080
	s_addc_u32 s11, s11, 0
	s_add_u32 s41, s14, 0x100
	v_mov_b32_e32 v2, 0
	s_addc_u32 s43, s15, 0
	s_mov_b32 s49, -2
	v_mov_b32_e32 v3, v2
	v_mov_b32_e32 v4, v2
	v_mov_b32_e32 v5, v2
	v_mov_b32_e32 v6, v2
	v_mov_b32_e32 v7, v2
	v_mov_b32_e32 v8, v2
	v_mov_b32_e32 v9, v2
	v_mov_b32_e32 v18, v2
	v_mov_b32_e32 v19, v2
	v_mov_b32_e32 v20, v2
	v_mov_b32_e32 v21, v2
	v_mov_b32_e32 v22, v2
	v_mov_b32_e32 v23, v2
	v_mov_b32_e32 v24, v2
	v_mov_b32_e32 v25, v2
	v_mov_b32_e32 v34, v2
	v_mov_b32_e32 v35, v2
	v_mov_b32_e32 v36, v2
	v_mov_b32_e32 v37, v2
	v_mov_b32_e32 v38, v2
	v_mov_b32_e32 v39, v2
	v_mov_b32_e32 v40, v2
	v_mov_b32_e32 v41, v2
	v_mov_b32_e32 v50, v2
	v_mov_b32_e32 v51, v2
	v_mov_b32_e32 v52, v2
	v_mov_b32_e32 v53, v2
	v_mov_b32_e32 v54, v2
	v_mov_b32_e32 v55, v2
	v_mov_b32_e32 v56, v2
	v_mov_b32_e32 v57, v2
	v_mov_b32_e32 v10, v2
	v_mov_b32_e32 v11, v2
	v_mov_b32_e32 v12, v2
	v_mov_b32_e32 v13, v2
	v_mov_b32_e32 v14, v2
	v_mov_b32_e32 v15, v2
	v_mov_b32_e32 v16, v2
	v_mov_b32_e32 v17, v2
	v_mov_b32_e32 v26, v2
	v_mov_b32_e32 v27, v2
	v_mov_b32_e32 v28, v2
	v_mov_b32_e32 v29, v2
	v_mov_b32_e32 v30, v2
	v_mov_b32_e32 v31, v2
	v_mov_b32_e32 v32, v2
	v_mov_b32_e32 v33, v2
	v_mov_b32_e32 v42, v2
	v_mov_b32_e32 v43, v2
	v_mov_b32_e32 v44, v2
	v_mov_b32_e32 v45, v2
	v_mov_b32_e32 v46, v2
	v_mov_b32_e32 v47, v2
	v_mov_b32_e32 v48, v2
	v_mov_b32_e32 v49, v2
	v_mov_b32_e32 v58, v2
	v_mov_b32_e32 v59, v2
	v_mov_b32_e32 v60, v2
	v_mov_b32_e32 v61, v2
	v_mov_b32_e32 v62, v2
	v_mov_b32_e32 v63, v2
	v_mov_b32_e32 v64, v2
	v_mov_b32_e32 v65, v2
	v_mov_b32_e32 v66, v2
	v_mov_b32_e32 v67, v2
	v_mov_b32_e32 v68, v2
	v_mov_b32_e32 v69, v2
	v_mov_b32_e32 v70, v2
	v_mov_b32_e32 v71, v2
	v_mov_b32_e32 v72, v2
	v_mov_b32_e32 v73, v2
	v_mov_b32_e32 v82, v2
	v_mov_b32_e32 v83, v2
	v_mov_b32_e32 v84, v2
	v_mov_b32_e32 v85, v2
	v_mov_b32_e32 v86, v2
	v_mov_b32_e32 v87, v2
	v_mov_b32_e32 v88, v2
	v_mov_b32_e32 v89, v2
	v_mov_b32_e32 v98, v2
	v_mov_b32_e32 v99, v2
	v_mov_b32_e32 v100, v2
	v_mov_b32_e32 v101, v2
	v_mov_b32_e32 v102, v2
	v_mov_b32_e32 v103, v2
	v_mov_b32_e32 v104, v2
	v_mov_b32_e32 v105, v2
	v_mov_b32_e32 v114, v2
	v_mov_b32_e32 v115, v2
	v_mov_b32_e32 v116, v2
	v_mov_b32_e32 v117, v2
	v_mov_b32_e32 v118, v2
	v_mov_b32_e32 v119, v2
	v_mov_b32_e32 v120, v2
	v_mov_b32_e32 v121, v2
	v_mov_b32_e32 v74, v2
	v_mov_b32_e32 v75, v2
	v_mov_b32_e32 v76, v2
	v_mov_b32_e32 v77, v2
	v_mov_b32_e32 v78, v2
	v_mov_b32_e32 v79, v2
	v_mov_b32_e32 v80, v2
	v_mov_b32_e32 v81, v2
	v_mov_b32_e32 v90, v2
	v_mov_b32_e32 v91, v2
	v_mov_b32_e32 v92, v2
	v_mov_b32_e32 v93, v2
	v_mov_b32_e32 v94, v2
	v_mov_b32_e32 v95, v2
	v_mov_b32_e32 v96, v2
	v_mov_b32_e32 v97, v2
	v_mov_b32_e32 v106, v2
	v_mov_b32_e32 v107, v2
	v_mov_b32_e32 v108, v2
	v_mov_b32_e32 v109, v2
	v_mov_b32_e32 v110, v2
	v_mov_b32_e32 v111, v2
	v_mov_b32_e32 v112, v2
	v_mov_b32_e32 v113, v2
	v_mov_b32_e32 v122, v2
	v_mov_b32_e32 v123, v2
	v_mov_b32_e32 v124, v2
	v_mov_b32_e32 v125, v2
	v_mov_b32_e32 v126, v2
	v_mov_b32_e32 v127, v2
	v_mov_b32_e32 v128, v2
	v_mov_b32_e32 v129, v2
	s_cmp_eq_u32 s73, 1
	s_cbranch_scc1 .LBB0_259
	s_add_u32 s14, s10, 0xfffc0080
	s_addc_u32 s15, s11, -1
	s_cmp_eq_u32 s49, 12
	s_cselect_b32 s27, s6, s15
	s_cselect_b32 s26, s36, s14
	v_add_u32_e32 v146, s33, v154
	s_cselect_b32 s15, s37, s43
	s_cselect_b32 s14, s40, s41
	s_add_i32 s51, 0, 0x14000
	ds_read_b128 v[142:145], v146
	ds_read_b128 v[158:161], v146 offset:1024
	ds_read_b128 v[162:165], v146 offset:2048
	ds_read_b128 v[166:169], v146 offset:3072
	v_add_u32_e32 v146, s51, v154
	ds_read_b128 v[170:173], v146
	ds_read_b128 v[174:177], v146 offset:1024
	ds_read_b128 v[178:181], v146 offset:2048
	ds_read_b128 v[182:185], v146 offset:3072
	v_lshl_add_u64 v[146:147], s[10:11], 0, v[138:139]
	s_add_i32 m0, s67, 0xc000
	ds_read_b128 v[186:189], v156
	ds_read_b128 v[190:193], v156 offset:1024
	ds_read_b128 v[194:197], v156 offset:2048
	ds_read_b128 v[198:201], v156 offset:3072
	ds_read_b128 v[202:205], v156 offset:4096
	ds_read_b128 v[206:209], v156 offset:5120
	ds_read_b128 v[210:213], v156 offset:6144
	ds_read_b128 v[214:217], v156 offset:7168
	v_lshl_add_u64 v[146:147], s[10:11], 0, v[140:141]
	s_add_i32 m0, s67, 0xe000
	s_nop 0
	s_waitcnt vmcnt(24)
	s_waitcnt lgkmcnt(0)
	s_barrier
	s_setprio 1
	s_waitcnt lgkmcnt(0)
	v_mfma_f32_16x16x32_bf16 v[126:129], v[142:145], v[186:189], v[126:129]
	v_mfma_f32_16x16x32_bf16 v[122:125], v[162:165], v[186:189], v[122:125]
	v_mfma_f32_16x16x32_bf16 v[110:113], v[142:145], v[194:197], v[110:113]
	v_mfma_f32_16x16x32_bf16 v[106:109], v[162:165], v[194:197], v[106:109]
	v_mfma_f32_16x16x32_bf16 v[94:97], v[142:145], v[202:205], v[94:97]
	v_mfma_f32_16x16x32_bf16 v[90:93], v[162:165], v[202:205], v[90:93]
	v_mfma_f32_16x16x32_bf16 v[78:81], v[142:145], v[210:213], v[78:81]
	v_mfma_f32_16x16x32_bf16 v[74:77], v[162:165], v[210:213], v[74:77]
	v_mfma_f32_16x16x32_bf16 v[126:129], v[158:161], v[190:193], v[126:129]
	v_mfma_f32_16x16x32_bf16 v[122:125], v[166:169], v[190:193], v[122:125]
	v_mfma_f32_16x16x32_bf16 v[110:113], v[158:161], v[198:201], v[110:113]
	v_mfma_f32_16x16x32_bf16 v[106:109], v[166:169], v[198:201], v[106:109]
	v_mfma_f32_16x16x32_bf16 v[94:97], v[158:161], v[206:209], v[94:97]
	v_mfma_f32_16x16x32_bf16 v[90:93], v[166:169], v[206:209], v[90:93]
	v_mfma_f32_16x16x32_bf16 v[78:81], v[158:161], v[214:217], v[78:81]
	v_mfma_f32_16x16x32_bf16 v[74:77], v[166:169], v[214:217], v[74:77]
	s_setprio 0
	s_setprio 1
	v_mfma_f32_16x16x32_bf16 v[118:121], v[170:173], v[186:189], v[118:121]
	v_mfma_f32_16x16x32_bf16 v[114:117], v[178:181], v[186:189], v[114:117]
	v_mfma_f32_16x16x32_bf16 v[102:105], v[170:173], v[194:197], v[102:105]
	v_mfma_f32_16x16x32_bf16 v[98:101], v[178:181], v[194:197], v[98:101]
	v_mfma_f32_16x16x32_bf16 v[86:89], v[170:173], v[202:205], v[86:89]
	v_mfma_f32_16x16x32_bf16 v[82:85], v[178:181], v[202:205], v[82:85]
	v_mfma_f32_16x16x32_bf16 v[70:73], v[170:173], v[210:213], v[70:73]
	v_mfma_f32_16x16x32_bf16 v[66:69], v[178:181], v[210:213], v[66:69]
	v_mfma_f32_16x16x32_bf16 v[118:121], v[174:177], v[190:193], v[118:121]
	v_mfma_f32_16x16x32_bf16 v[114:117], v[182:185], v[190:193], v[114:117]
	v_mfma_f32_16x16x32_bf16 v[102:105], v[174:177], v[198:201], v[102:105]
	v_mfma_f32_16x16x32_bf16 v[98:101], v[182:185], v[198:201], v[98:101]
	v_mfma_f32_16x16x32_bf16 v[86:89], v[174:177], v[206:209], v[86:89]
	v_mfma_f32_16x16x32_bf16 v[82:85], v[182:185], v[206:209], v[82:85]
	v_mfma_f32_16x16x32_bf16 v[70:73], v[174:177], v[214:217], v[70:73]
	v_mfma_f32_16x16x32_bf16 v[66:69], v[182:185], v[214:217], v[66:69]
	s_setprio 0
	s_barrier
	s_add_i32 s58, s33, s66
	v_lshl_add_u64 v[146:147], s[14:15], 0, v[132:133]
	s_mov_b32 m0, s58
	ds_read_b128 v[186:189], v156 offset:16384
	ds_read_b128 v[190:193], v156 offset:17408
	ds_read_b128 v[194:197], v156 offset:18432
	ds_read_b128 v[198:201], v156 offset:19456
	ds_read_b128 v[202:205], v156 offset:20480
	ds_read_b128 v[206:209], v156 offset:21504
	ds_read_b128 v[210:213], v156 offset:22528
	ds_read_b128 v[214:217], v156 offset:23552
	global_load_lds_dwordx4 v[146:147], off
	s_add_i32 m0, s58, 0x2000
	s_add_u32 s58, s14, 0x40000
	v_lshl_add_u64 v[148:149], s[14:15], 0, v[136:137]
	s_addc_u32 s59, s15, 0
	s_add_i32 s51, s51, s66
	global_load_lds_dwordx4 v[148:149], off
	v_lshl_add_u64 v[150:151], s[58:59], 0, v[132:133]
	s_mov_b32 m0, s51
	v_lshl_add_u64 v[152:153], s[26:27], 0, v[134:135]
	global_load_lds_dwordx4 v[150:151], off
	v_lshl_add_u64 v[150:151], s[58:59], 0, v[136:137]
	s_add_i32 m0, s51, 0x2000
	s_nop 0
	global_load_lds_dwordx4 v[150:151], off
	v_lshl_add_u64 v[150:151], s[26:27], 0, v[130:131]
	s_mov_b32 m0, s67
	s_nop 0
	global_load_lds_dwordx4 v[150:151], off
	s_mov_b32 m0, s68
	s_nop 0
	global_load_lds_dwordx4 v[152:153], off
	s_waitcnt vmcnt(24)
	s_waitcnt lgkmcnt(0)
	s_barrier
	s_setprio 1
	s_waitcnt lgkmcnt(0)
	v_mfma_f32_16x16x32_bf16 v[62:65], v[142:145], v[186:189], v[62:65]
	v_mfma_f32_16x16x32_bf16 v[58:61], v[162:165], v[186:189], v[58:61]
	v_mfma_f32_16x16x32_bf16 v[46:49], v[142:145], v[194:197], v[46:49]
	v_mfma_f32_16x16x32_bf16 v[42:45], v[162:165], v[194:197], v[42:45]
	v_mfma_f32_16x16x32_bf16 v[30:33], v[142:145], v[202:205], v[30:33]
	v_mfma_f32_16x16x32_bf16 v[26:29], v[162:165], v[202:205], v[26:29]
	v_mfma_f32_16x16x32_bf16 v[14:17], v[142:145], v[210:213], v[14:17]
	v_mfma_f32_16x16x32_bf16 v[10:13], v[162:165], v[210:213], v[10:13]
	v_mfma_f32_16x16x32_bf16 v[62:65], v[158:161], v[190:193], v[62:65]
	v_mfma_f32_16x16x32_bf16 v[58:61], v[166:169], v[190:193], v[58:61]
	v_mfma_f32_16x16x32_bf16 v[46:49], v[158:161], v[198:201], v[46:49]
	v_mfma_f32_16x16x32_bf16 v[42:45], v[166:169], v[198:201], v[42:45]
	v_mfma_f32_16x16x32_bf16 v[30:33], v[158:161], v[206:209], v[30:33]
	v_mfma_f32_16x16x32_bf16 v[26:29], v[166:169], v[206:209], v[26:29]
	v_mfma_f32_16x16x32_bf16 v[14:17], v[158:161], v[214:217], v[14:17]
	v_mfma_f32_16x16x32_bf16 v[10:13], v[166:169], v[214:217], v[10:13]
	s_setprio 0
	s_setprio 1
	v_mfma_f32_16x16x32_bf16 v[54:57], v[170:173], v[186:189], v[54:57]
	v_mfma_f32_16x16x32_bf16 v[50:53], v[178:181], v[186:189], v[50:53]
	v_mfma_f32_16x16x32_bf16 v[38:41], v[170:173], v[194:197], v[38:41]
	v_mfma_f32_16x16x32_bf16 v[34:37], v[178:181], v[194:197], v[34:37]
	v_mfma_f32_16x16x32_bf16 v[22:25], v[170:173], v[202:205], v[22:25]
	v_mfma_f32_16x16x32_bf16 v[18:21], v[178:181], v[202:205], v[18:21]
	v_mfma_f32_16x16x32_bf16 v[6:9], v[170:173], v[210:213], v[6:9]
	v_mfma_f32_16x16x32_bf16 v[2:5], v[178:181], v[210:213], v[2:5]
	v_mfma_f32_16x16x32_bf16 v[54:57], v[174:177], v[190:193], v[54:57]
	v_mfma_f32_16x16x32_bf16 v[50:53], v[182:185], v[190:193], v[50:53]
	v_mfma_f32_16x16x32_bf16 v[38:41], v[174:177], v[198:201], v[38:41]
	v_mfma_f32_16x16x32_bf16 v[34:37], v[182:185], v[198:201], v[34:37]
	v_mfma_f32_16x16x32_bf16 v[22:25], v[174:177], v[206:209], v[22:25]
	v_mfma_f32_16x16x32_bf16 v[18:21], v[182:185], v[206:209], v[18:21]
	v_mfma_f32_16x16x32_bf16 v[6:9], v[174:177], v[214:217], v[6:9]
	v_mfma_f32_16x16x32_bf16 v[2:5], v[182:185], v[214:217], v[2:5]
	s_setprio 0
	s_barrier
	s_add_i32 s51, 0, 0x18000
	v_add_u32_e32 v157, s51, v154
	s_add_i32 s58, 0, 0x1c000
	ds_read_b128 v[142:145], v157
	ds_read_b128 v[158:161], v157 offset:1024
	ds_read_b128 v[162:165], v157 offset:2048
	ds_read_b128 v[166:169], v157 offset:3072
	v_add_u32_e32 v157, s58, v154
	ds_read_b128 v[170:173], v157
	ds_read_b128 v[174:177], v157 offset:1024
	ds_read_b128 v[178:181], v157 offset:2048
	ds_read_b128 v[182:185], v157 offset:3072
	s_add_u32 s26, s26, 0x40000
	s_addc_u32 s27, s27, 0
	s_mov_b32 m0, s69
	v_lshl_add_u64 v[218:219], s[26:27], 0, v[130:131]
	ds_read_b128 v[186:189], v156 offset:32768
	ds_read_b128 v[190:193], v156 offset:33792
	ds_read_b128 v[194:197], v156 offset:34816
	ds_read_b128 v[198:201], v156 offset:35840
	ds_read_b128 v[202:205], v156 offset:36864
	ds_read_b128 v[206:209], v156 offset:37888
	ds_read_b128 v[210:213], v156 offset:38912
	ds_read_b128 v[214:217], v156 offset:39936
	global_load_lds_dwordx4 v[218:219], off
	v_lshl_add_u64 v[218:219], s[26:27], 0, v[134:135]
	s_mov_b32 m0, s70
	s_nop 0
	global_load_lds_dwordx4 v[218:219], off
	s_waitcnt vmcnt(24)
	s_waitcnt lgkmcnt(0)
	s_barrier
	s_setprio 1
	s_waitcnt lgkmcnt(0)
	v_mfma_f32_16x16x32_bf16 v[126:129], v[142:145], v[186:189], v[126:129]
	v_mfma_f32_16x16x32_bf16 v[122:125], v[162:165], v[186:189], v[122:125]
	v_mfma_f32_16x16x32_bf16 v[110:113], v[142:145], v[194:197], v[110:113]
	v_mfma_f32_16x16x32_bf16 v[106:109], v[162:165], v[194:197], v[106:109]
	v_mfma_f32_16x16x32_bf16 v[94:97], v[142:145], v[202:205], v[94:97]
	v_mfma_f32_16x16x32_bf16 v[90:93], v[162:165], v[202:205], v[90:93]
	v_mfma_f32_16x16x32_bf16 v[78:81], v[142:145], v[210:213], v[78:81]
	v_mfma_f32_16x16x32_bf16 v[74:77], v[162:165], v[210:213], v[74:77]
	v_mfma_f32_16x16x32_bf16 v[126:129], v[158:161], v[190:193], v[126:129]
	v_mfma_f32_16x16x32_bf16 v[122:125], v[166:169], v[190:193], v[122:125]
	v_mfma_f32_16x16x32_bf16 v[110:113], v[158:161], v[198:201], v[110:113]
	v_mfma_f32_16x16x32_bf16 v[106:109], v[166:169], v[198:201], v[106:109]
	v_mfma_f32_16x16x32_bf16 v[94:97], v[158:161], v[206:209], v[94:97]
	v_mfma_f32_16x16x32_bf16 v[90:93], v[166:169], v[206:209], v[90:93]
	v_mfma_f32_16x16x32_bf16 v[78:81], v[158:161], v[214:217], v[78:81]
	v_mfma_f32_16x16x32_bf16 v[74:77], v[166:169], v[214:217], v[74:77]
	s_setprio 0
	s_setprio 1
	v_mfma_f32_16x16x32_bf16 v[118:121], v[170:173], v[186:189], v[118:121]
	v_mfma_f32_16x16x32_bf16 v[114:117], v[178:181], v[186:189], v[114:117]
	v_mfma_f32_16x16x32_bf16 v[102:105], v[170:173], v[194:197], v[102:105]
	v_mfma_f32_16x16x32_bf16 v[98:101], v[178:181], v[194:197], v[98:101]
	v_mfma_f32_16x16x32_bf16 v[86:89], v[170:173], v[202:205], v[86:89]
	v_mfma_f32_16x16x32_bf16 v[82:85], v[178:181], v[202:205], v[82:85]
	v_mfma_f32_16x16x32_bf16 v[70:73], v[170:173], v[210:213], v[70:73]
	v_mfma_f32_16x16x32_bf16 v[66:69], v[178:181], v[210:213], v[66:69]
	v_mfma_f32_16x16x32_bf16 v[118:121], v[174:177], v[190:193], v[118:121]
	v_mfma_f32_16x16x32_bf16 v[114:117], v[182:185], v[190:193], v[114:117]
	v_mfma_f32_16x16x32_bf16 v[102:105], v[174:177], v[198:201], v[102:105]
	v_mfma_f32_16x16x32_bf16 v[98:101], v[182:185], v[198:201], v[98:101]
	v_mfma_f32_16x16x32_bf16 v[86:89], v[174:177], v[206:209], v[86:89]
	v_mfma_f32_16x16x32_bf16 v[82:85], v[182:185], v[206:209], v[82:85]
	v_mfma_f32_16x16x32_bf16 v[70:73], v[174:177], v[214:217], v[70:73]
	v_mfma_f32_16x16x32_bf16 v[66:69], v[182:185], v[214:217], v[66:69]
	s_setprio 0
	s_barrier
	s_add_i32 s26, s51, s66
	v_lshl_add_u64 v[146:147], v[146:147], 0, s[24:25]
	s_mov_b32 m0, s26
	ds_read_b128 v[186:189], v156 offset:49152
	ds_read_b128 v[190:193], v156 offset:50176
	ds_read_b128 v[194:197], v156 offset:51200
	ds_read_b128 v[198:201], v156 offset:52224
	ds_read_b128 v[202:205], v156 offset:53248
	ds_read_b128 v[206:209], v156 offset:54272
	ds_read_b128 v[210:213], v156 offset:55296
	ds_read_b128 v[214:217], v156 offset:56320
	global_load_lds_dwordx4 v[146:147], off
	s_add_i32 m0, s26, 0x2000
	s_add_u32 s14, s14, 0x40080
	v_lshl_add_u64 v[146:147], v[148:149], 0, s[24:25]
	s_addc_u32 s15, s15, 0
	s_add_i32 s26, s58, s66
	global_load_lds_dwordx4 v[146:147], off
	v_lshl_add_u64 v[146:147], s[14:15], 0, v[132:133]
	s_mov_b32 m0, s26
	s_nop 0
	global_load_lds_dwordx4 v[146:147], off
	v_lshl_add_u64 v[146:147], s[14:15], 0, v[136:137]
	s_add_i32 m0, s26, 0x2000
	s_nop 0
	global_load_lds_dwordx4 v[146:147], off
	v_lshl_add_u64 v[146:147], v[150:151], 0, s[24:25]
	s_mov_b32 m0, s71
	s_nop 0
	global_load_lds_dwordx4 v[146:147], off
	v_lshl_add_u64 v[146:147], v[152:153], 0, s[24:25]
	s_mov_b32 m0, s72
	s_nop 0
	global_load_lds_dwordx4 v[146:147], off
	s_waitcnt vmcnt(8)
	s_waitcnt lgkmcnt(0)
	s_barrier
	s_setprio 1
	s_waitcnt lgkmcnt(0)
	v_mfma_f32_16x16x32_bf16 v[62:65], v[142:145], v[186:189], v[62:65]
	v_mfma_f32_16x16x32_bf16 v[58:61], v[162:165], v[186:189], v[58:61]
	v_mfma_f32_16x16x32_bf16 v[46:49], v[142:145], v[194:197], v[46:49]
	v_mfma_f32_16x16x32_bf16 v[42:45], v[162:165], v[194:197], v[42:45]
	v_mfma_f32_16x16x32_bf16 v[30:33], v[142:145], v[202:205], v[30:33]
	v_mfma_f32_16x16x32_bf16 v[26:29], v[162:165], v[202:205], v[26:29]
	v_mfma_f32_16x16x32_bf16 v[14:17], v[142:145], v[210:213], v[14:17]
	v_mfma_f32_16x16x32_bf16 v[10:13], v[162:165], v[210:213], v[10:13]
	v_mfma_f32_16x16x32_bf16 v[62:65], v[158:161], v[190:193], v[62:65]
	v_mfma_f32_16x16x32_bf16 v[58:61], v[166:169], v[190:193], v[58:61]
	v_mfma_f32_16x16x32_bf16 v[46:49], v[158:161], v[198:201], v[46:49]
	v_mfma_f32_16x16x32_bf16 v[42:45], v[166:169], v[198:201], v[42:45]
	v_mfma_f32_16x16x32_bf16 v[30:33], v[158:161], v[206:209], v[30:33]
	v_mfma_f32_16x16x32_bf16 v[26:29], v[166:169], v[206:209], v[26:29]
	v_mfma_f32_16x16x32_bf16 v[14:17], v[158:161], v[214:217], v[14:17]
	v_mfma_f32_16x16x32_bf16 v[10:13], v[166:169], v[214:217], v[10:13]
	s_setprio 0
	s_setprio 1
	v_mfma_f32_16x16x32_bf16 v[54:57], v[170:173], v[186:189], v[54:57]
	v_mfma_f32_16x16x32_bf16 v[50:53], v[178:181], v[186:189], v[50:53]
	v_mfma_f32_16x16x32_bf16 v[38:41], v[170:173], v[194:197], v[38:41]
	v_mfma_f32_16x16x32_bf16 v[34:37], v[178:181], v[194:197], v[34:37]
	v_mfma_f32_16x16x32_bf16 v[22:25], v[170:173], v[202:205], v[22:25]
	v_mfma_f32_16x16x32_bf16 v[18:21], v[178:181], v[202:205], v[18:21]
	v_mfma_f32_16x16x32_bf16 v[6:9], v[170:173], v[210:213], v[6:9]
	v_mfma_f32_16x16x32_bf16 v[2:5], v[178:181], v[210:213], v[2:5]
	v_mfma_f32_16x16x32_bf16 v[54:57], v[174:177], v[190:193], v[54:57]
	v_mfma_f32_16x16x32_bf16 v[50:53], v[182:185], v[190:193], v[50:53]
	v_mfma_f32_16x16x32_bf16 v[38:41], v[174:177], v[198:201], v[38:41]
	v_mfma_f32_16x16x32_bf16 v[34:37], v[182:185], v[198:201], v[34:37]
	v_mfma_f32_16x16x32_bf16 v[22:25], v[174:177], v[206:209], v[22:25]
	v_mfma_f32_16x16x32_bf16 v[18:21], v[182:185], v[206:209], v[18:21]
	v_mfma_f32_16x16x32_bf16 v[6:9], v[174:177], v[214:217], v[6:9]
	v_mfma_f32_16x16x32_bf16 v[2:5], v[182:185], v[214:217], v[2:5]
	s_setprio 0
	s_barrier
	s_add_i32 s49, s49, 2
	s_add_u32 s10, s10, 0x100
	s_addc_u32 s11, s11, 0
	s_add_u32 s41, s41, 0x100
	s_addc_u32 s43, s43, 0

.LBB0_285:
	s_and_b64 vcc, exec, s[56:57]
	s_cbranch_vccz .Lei_nopre
	s_add_u32 s14, s52, 0x40080
	s_addc_u32 s15, s53, 0
	v_lshl_add_u64 v[146:147], s[14:15], 0, v[138:139]
	s_add_i32 m0, s67, 0xc000
	v_lshl_add_u64 v[148:149], s[14:15], 0, v[140:141]
	global_load_lds_dwordx4 v[146:147], off
	s_add_i32 m0, s67, 0xe000
	s_nop 0
	global_load_lds_dwordx4 v[148:149], off
.Lei_nopre:
	s_add_u32 s10, s12, s10
	s_addc_u32 s11, s13, s11
	v_add_u32_e32 v142, s6, v155
	v_add_u32_e32 v144, s26, v1
	v_ashrrev_i32_e32 v143, 31, v142
	v_mul_lo_u32 v144, v144, s58
	v_mov_b32_e32 v145, 0
	s_lshl_b32 s14, s58, 5
	s_mov_b32 s15, 0
	s_lshl_b32 s36, s58, 8
	s_mov_b32 s37, 0
	v_lshl_add_u64 v[142:143], v[142:143], 1, s[10:11]
	v_lshl_add_u64 v[182:183], v[144:145], 1, v[142:143]
	v_lshl_add_u64 v[190:191], s[36:37], 0, v[182:183]
	v_lshl_add_u64 v[184:185], s[14:15], 0, v[182:183]
	v_lshl_add_u64 v[192:193], s[14:15], 0, v[190:191]
	v_lshl_add_u64 v[186:187], s[14:15], 0, v[184:185]
	v_lshl_add_u64 v[194:195], s[14:15], 0, v[192:193]
	v_lshl_add_u64 v[188:189], s[14:15], 0, v[186:187]
	v_lshl_add_u64 v[196:197], s[14:15], 0, v[194:195]
	s_cmp_eq_u32 s60, 1.0
	s_cbranch_scc1 .Lei_noscale
	v_pk_mul_f32 v[2:3], v[2:3], s[60:61] op_sel_hi:[1,0]
	v_pk_mul_f32 v[4:5], v[4:5], s[60:61] op_sel_hi:[1,0]
	v_pk_mul_f32 v[6:7], v[6:7], s[60:61] op_sel_hi:[1,0]
	v_pk_mul_f32 v[8:9], v[8:9], s[60:61] op_sel_hi:[1,0]
	v_pk_mul_f32 v[10:11], v[10:11], s[60:61] op_sel_hi:[1,0]
	v_pk_mul_f32 v[12:13], v[12:13], s[60:61] op_sel_hi:[1,0]
	v_pk_mul_f32 v[14:15], v[14:15], s[60:61] op_sel_hi:[1,0]
	v_pk_mul_f32 v[16:17], v[16:17], s[60:61] op_sel_hi:[1,0]
	v_pk_mul_f32 v[18:19], v[18:19], s[60:61] op_sel_hi:[1,0]
	v_pk_mul_f32 v[20:21], v[20:21], s[60:61] op_sel_hi:[1,0]
	v_pk_mul_f32 v[22:23], v[22:23], s[60:61] op_sel_hi:[1,0]
	v_pk_mul_f32 v[24:25], v[24:25], s[60:61] op_sel_hi:[1,0]
	v_pk_mul_f32 v[26:27], v[26:27], s[60:61] op_sel_hi:[1,0]
	v_pk_mul_f32 v[28:29], v[28:29], s[60:61] op_sel_hi:[1,0]
	v_pk_mul_f32 v[30:31], v[30:31], s[60:61] op_sel_hi:[1,0]
	v_pk_mul_f32 v[32:33], v[32:33], s[60:61] op_sel_hi:[1,0]
	v_pk_mul_f32 v[34:35], v[34:35], s[60:61] op_sel_hi:[1,0]
	v_pk_mul_f32 v[36:37], v[36:37], s[60:61] op_sel_hi:[1,0]
	v_pk_mul_f32 v[38:39], v[38:39], s[60:61] op_sel_hi:[1,0]
	v_pk_mul_f32 v[40:41], v[40:41], s[60:61] op_sel_hi:[1,0]
	v_pk_mul_f32 v[42:43], v[42:43], s[60:61] op_sel_hi:[1,0]
	v_pk_mul_f32 v[44:45], v[44:45], s[60:61] op_sel_hi:[1,0]
	v_pk_mul_f32 v[46:47], v[46:47], s[60:61] op_sel_hi:[1,0]
	v_pk_mul_f32 v[48:49], v[48:49], s[60:61] op_sel_hi:[1,0]
	v_pk_mul_f32 v[50:51], v[50:51], s[60:61] op_sel_hi:[1,0]
	v_pk_mul_f32 v[52:53], v[52:53], s[60:61] op_sel_hi:[1,0]
	v_pk_mul_f32 v[54:55], v[54:55], s[60:61] op_sel_hi:[1,0]
	v_pk_mul_f32 v[56:57], v[56:57], s[60:61] op_sel_hi:[1,0]
	v_pk_mul_f32 v[58:59], v[58:59], s[60:61] op_sel_hi:[1,0]
	v_pk_mul_f32 v[60:61], v[60:61], s[60:61] op_sel_hi:[1,0]
	v_pk_mul_f32 v[62:63], v[62:63], s[60:61] op_sel_hi:[1,0]
	v_pk_mul_f32 v[64:65], v[64:65], s[60:61] op_sel_hi:[1,0]
	v_pk_mul_f32 v[66:67], v[66:67], s[60:61] op_sel_hi:[1,0]
	v_pk_mul_f32 v[68:69], v[68:69], s[60:61] op_sel_hi:[1,0]
	v_pk_mul_f32 v[70:71], v[70:71], s[60:61] op_sel_hi:[1,0]
	v_pk_mul_f32 v[72:73], v[72:73], s[60:61] op_sel_hi:[1,0]
	v_pk_mul_f32 v[74:75], v[74:75], s[60:61] op_sel_hi:[1,0]
	v_pk_mul_f32 v[76:77], v[76:77], s[60:61] op_sel_hi:[1,0]
	v_pk_mul_f32 v[78:79], v[78:79], s[60:61] op_sel_hi:[1,0]
	v_pk_mul_f32 v[80:81], v[80:81], s[60:61] op_sel_hi:[1,0]
	v_pk_mul_f32 v[82:83], v[82:83], s[60:61] op_sel_hi:[1,0]
	v_pk_mul_f32 v[84:85], v[84:85], s[60:61] op_sel_hi:[1,0]
	v_pk_mul_f32 v[86:87], v[86:87], s[60:61] op_sel_hi:[1,0]
	v_pk_mul_f32 v[88:89], v[88:89], s[60:61] op_sel_hi:[1,0]
	v_pk_mul_f32 v[90:91], v[90:91], s[60:61] op_sel_hi:[1,0]
	v_pk_mul_f32 v[92:93], v[92:93], s[60:61] op_sel_hi:[1,0]
	v_pk_mul_f32 v[94:95], v[94:95], s[60:61] op_sel_hi:[1,0]
	v_pk_mul_f32 v[96:97], v[96:97], s[60:61] op_sel_hi:[1,0]
	v_pk_mul_f32 v[98:99], v[98:99], s[60:61] op_sel_hi:[1,0]
	v_pk_mul_f32 v[100:101], v[100:101], s[60:61] op_sel_hi:[1,0]
	v_pk_mul_f32 v[102:103], v[102:103], s[60:61] op_sel_hi:[1,0]
	v_pk_mul_f32 v[104:105], v[104:105], s[60:61] op_sel_hi:[1,0]
	v_pk_mul_f32 v[106:107], v[106:107], s[60:61] op_sel_hi:[1,0]
	v_pk_mul_f32 v[108:109], v[108:109], s[60:61] op_sel_hi:[1,0]
	v_pk_mul_f32 v[110:111], v[110:111], s[60:61] op_sel_hi:[1,0]
	v_pk_mul_f32 v[112:113], v[112:113], s[60:61] op_sel_hi:[1,0]
	v_pk_mul_f32 v[114:115], v[114:115], s[60:61] op_sel_hi:[1,0]
	v_pk_mul_f32 v[116:117], v[116:117], s[60:61] op_sel_hi:[1,0]
	v_pk_mul_f32 v[118:119], v[118:119], s[60:61] op_sel_hi:[1,0]
	v_pk_mul_f32 v[120:121], v[120:121], s[60:61] op_sel_hi:[1,0]
	v_pk_mul_f32 v[122:123], v[122:123], s[60:61] op_sel_hi:[1,0]
	v_pk_mul_f32 v[124:125], v[124:125], s[60:61] op_sel_hi:[1,0]
	v_pk_mul_f32 v[126:127], v[126:127], s[60:61] op_sel_hi:[1,0]
	v_pk_mul_f32 v[128:129], v[128:129], s[60:61] op_sel_hi:[1,0]
.Lei_noscale:
	s_cmp_eq_u32 s27, 0
	s_cbranch_scc1 .Lei_plain
	s_mov_b32 s40, 0xbfb8aa3b
	s_mov_b32 s41, s40
	s_mov_b32 s42, 1.0
	s_mov_b32 s43, 1.0
	s_cmp_eq_u32 s27, 1
	s_cbranch_scc1 .Lei_sig
	v_pk_mul_f32 v[158:159], v[126:127], s[40:41]
	v_pk_mul_f32 v[160:161], v[128:129], s[40:41]
	v_pk_mul_f32 v[162:163], v[122:123], s[40:41]
	v_pk_mul_f32 v[164:165], v[124:125], s[40:41]
	v_exp_f32_e32 v158, v158
	v_exp_f32_e32 v159, v159
	v_exp_f32_e32 v160, v160
	v_exp_f32_e32 v161, v161
	v_exp_f32_e32 v162, v162
	v_exp_f32_e32 v163, v163
	v_exp_f32_e32 v164, v164
	v_exp_f32_e32 v165, v165
	v_pk_add_f32 v[158:159], v[158:159], s[42:43]
	v_pk_add_f32 v[160:161], v[160:161], s[42:43]
	v_pk_add_f32 v[162:163], v[162:163], s[42:43]
	v_pk_add_f32 v[164:165], v[164:165], s[42:43]
	v_rcp_f32_e32 v158, v158
	v_rcp_f32_e32 v159, v159
	v_rcp_f32_e32 v160, v160
	v_rcp_f32_e32 v161, v161
	v_rcp_f32_e32 v162, v162
	v_rcp_f32_e32 v163, v163
	v_rcp_f32_e32 v164, v164
	v_rcp_f32_e32 v165, v165
	v_pk_mul_f32 v[158:159], v[126:127], v[158:159]
	v_pk_mul_f32 v[160:161], v[128:129], v[160:161]
	v_pk_mul_f32 v[162:163], v[122:123], v[162:163]
	v_pk_mul_f32 v[164:165], v[124:125], v[164:165]
	v_cvt_pk_bf16_f32 v174, v158, v159
	v_cvt_pk_bf16_f32 v175, v160, v161
	v_cvt_pk_bf16_f32 v176, v162, v163
	v_cvt_pk_bf16_f32 v177, v164, v165
	global_store_dwordx4 v[182:183], v[174:177], off
	v_pk_mul_f32 v[166:167], v[118:119], s[40:41]
	v_pk_mul_f32 v[168:169], v[120:121], s[40:41]
	v_pk_mul_f32 v[170:171], v[114:115], s[40:41]
	v_pk_mul_f32 v[172:173], v[116:117], s[40:41]
	v_exp_f32_e32 v166, v166
	v_exp_f32_e32 v167, v167
	v_exp_f32_e32 v168, v168
	v_exp_f32_e32 v169, v169
	v_exp_f32_e32 v170, v170
	v_exp_f32_e32 v171, v171
	v_exp_f32_e32 v172, v172
	v_exp_f32_e32 v173, v173
	v_pk_add_f32 v[166:167], v[166:167], s[42:43]
	v_pk_add_f32 v[168:169], v[168:169], s[42:43]
	v_pk_add_f32 v[170:171], v[170:171], s[42:43]
	v_pk_add_f32 v[172:173], v[172:173], s[42:43]
	v_rcp_f32_e32 v166, v166
	v_rcp_f32_e32 v167, v167
	v_rcp_f32_e32 v168, v168
	v_rcp_f32_e32 v169, v169
	v_rcp_f32_e32 v170, v170
	v_rcp_f32_e32 v171, v171
	v_rcp_f32_e32 v172, v172
	v_rcp_f32_e32 v173, v173
	v_pk_mul_f32 v[166:167], v[118:119], v[166:167]
	v_pk_mul_f32 v[168:169], v[120:121], v[168:169]
	v_pk_mul_f32 v[170:171], v[114:115], v[170:171]
	v_pk_mul_f32 v[172:173], v[116:117], v[172:173]
	v_cvt_pk_bf16_f32 v178, v166, v167
	v_cvt_pk_bf16_f32 v179, v168, v169
	v_cvt_pk_bf16_f32 v180, v170, v171
	v_cvt_pk_bf16_f32 v181, v172, v173
	global_store_dwordx4 v[182:183], v[178:181], off offset:256
	v_pk_mul_f32 v[158:159], v[110:111], s[40:41]
	v_pk_mul_f32 v[160:161], v[112:113], s[40:41]
	v_pk_mul_f32 v[162:163], v[106:107], s[40:41]
	v_pk_mul_f32 v[164:165], v[108:109], s[40:41]
	v_exp_f32_e32 v158, v158
	v_exp_f32_e32 v159, v159
	v_exp_f32_e32 v160, v160
	v_exp_f32_e32 v161, v161
	v_exp_f32_e32 v162, v162
	v_exp_f32_e32 v163, v163
	v_exp_f32_e32 v164, v164
	v_exp_f32_e32 v165, v165
	v_pk_add_f32 v[158:159], v[158:159], s[42:43]
	v_pk_add_f32 v[160:161], v[160:161], s[42:43]
	v_pk_add_f32 v[162:163], v[162:163], s[42:43]
	v_pk_add_f32 v[164:165], v[164:165], s[42:43]
	v_rcp_f32_e32 v158, v158
	v_rcp_f32_e32 v159, v159
	v_rcp_f32_e32 v160, v160
	v_rcp_f32_e32 v161, v161
	v_rcp_f32_e32 v162, v162
	v_rcp_f32_e32 v163, v163
	v_rcp_f32_e32 v164, v164
	v_rcp_f32_e32 v165, v165
	v_pk_mul_f32 v[158:159], v[110:111], v[158:159]
	v_pk_mul_f32 v[160:161], v[112:113], v[160:161]
	v_pk_mul_f32 v[162:163], v[106:107], v[162:163]
	v_pk_mul_f32 v[164:165], v[108:109], v[164:165]
	v_cvt_pk_bf16_f32 v174, v158, v159
	v_cvt_pk_bf16_f32 v175, v160, v161
	v_cvt_pk_bf16_f32 v176, v162, v163
	v_cvt_pk_bf16_f32 v177, v164, v165
	global_store_dwordx4 v[184:185], v[174:177], off
	v_pk_mul_f32 v[166:167], v[102:103], s[40:41]
	v_pk_mul_f32 v[168:169], v[104:105], s[40:41]
	v_pk_mul_f32 v[170:171], v[98:99], s[40:41]
	v_pk_mul_f32 v[172:173], v[100:101], s[40:41]
	v_exp_f32_e32 v166, v166
	v_exp_f32_e32 v167, v167
	v_exp_f32_e32 v168, v168
	v_exp_f32_e32 v169, v169
	v_exp_f32_e32 v170, v170
	v_exp_f32_e32 v171, v171
	v_exp_f32_e32 v172, v172
	v_exp_f32_e32 v173, v173
	v_pk_add_f32 v[166:167], v[166:167], s[42:43]
	v_pk_add_f32 v[168:169], v[168:169], s[42:43]
	v_pk_add_f32 v[170:171], v[170:171], s[42:43]
	v_pk_add_f32 v[172:173], v[172:173], s[42:43]
	v_rcp_f32_e32 v166, v166
	v_rcp_f32_e32 v167, v167
	v_rcp_f32_e32 v168, v168
	v_rcp_f32_e32 v169, v169
	v_rcp_f32_e32 v170, v170
	v_rcp_f32_e32 v171, v171
	v_rcp_f32_e32 v172, v172
	v_rcp_f32_e32 v173, v173
	v_pk_mul_f32 v[166:167], v[102:103], v[166:167]
	v_pk_mul_f32 v[168:169], v[104:105], v[168:169]
	v_pk_mul_f32 v[170:171], v[98:99], v[170:171]
	v_pk_mul_f32 v[172:173], v[100:101], v[172:173]
	v_cvt_pk_bf16_f32 v178, v166, v167
	v_cvt_pk_bf16_f32 v179, v168, v169
	v_cvt_pk_bf16_f32 v180, v170, v171
	v_cvt_pk_bf16_f32 v181, v172, v173
	global_store_dwordx4 v[184:185], v[178:181], off offset:256
	v_pk_mul_f32 v[158:159], v[94:95], s[40:41]
	v_pk_mul_f32 v[160:161], v[96:97], s[40:41]
	v_pk_mul_f32 v[162:163], v[90:91], s[40:41]
	v_pk_mul_f32 v[164:165], v[92:93], s[40:41]
	v_exp_f32_e32 v158, v158
	v_exp_f32_e32 v159, v159
	v_exp_f32_e32 v160, v160
	v_exp_f32_e32 v161, v161
	v_exp_f32_e32 v162, v162
	v_exp_f32_e32 v163, v163
	v_exp_f32_e32 v164, v164
	v_exp_f32_e32 v165, v165
	v_pk_add_f32 v[158:159], v[158:159], s[42:43]
	v_pk_add_f32 v[160:161], v[160:161], s[42:43]
	v_pk_add_f32 v[162:163], v[162:163], s[42:43]
	v_pk_add_f32 v[164:165], v[164:165], s[42:43]
	v_rcp_f32_e32 v158, v158
	v_rcp_f32_e32 v159, v159
	v_rcp_f32_e32 v160, v160
	v_rcp_f32_e32 v161, v161
	v_rcp_f32_e32 v162, v162
	v_rcp_f32_e32 v163, v163
	v_rcp_f32_e32 v164, v164
	v_rcp_f32_e32 v165, v165
	v_pk_mul_f32 v[158:159], v[94:95], v[158:159]
	v_pk_mul_f32 v[160:161], v[96:97], v[160:161]
	v_pk_mul_f32 v[162:163], v[90:91], v[162:163]
	v_pk_mul_f32 v[164:165], v[92:93], v[164:165]
	v_cvt_pk_bf16_f32 v174, v158, v159
	v_cvt_pk_bf16_f32 v175, v160, v161
	v_cvt_pk_bf16_f32 v176, v162, v163
	v_cvt_pk_bf16_f32 v177, v164, v165
	global_store_dwordx4 v[186:187], v[174:177], off
	v_pk_mul_f32 v[166:167], v[86:87], s[40:41]
	v_pk_mul_f32 v[168:169], v[88:89], s[40:41]
	v_pk_mul_f32 v[170:171], v[82:83], s[40:41]
	v_pk_mul_f32 v[172:173], v[84:85], s[40:41]
	v_exp_f32_e32 v166, v166
	v_exp_f32_e32 v167, v167
	v_exp_f32_e32 v168, v168
	v_exp_f32_e32 v169, v169
	v_exp_f32_e32 v170, v170
	v_exp_f32_e32 v171, v171
	v_exp_f32_e32 v172, v172
	v_exp_f32_e32 v173, v173
	v_pk_add_f32 v[166:167], v[166:167], s[42:43]
	v_pk_add_f32 v[168:169], v[168:169], s[42:43]
	v_pk_add_f32 v[170:171], v[170:171], s[42:43]
	v_pk_add_f32 v[172:173], v[172:173], s[42:43]
	v_rcp_f32_e32 v166, v166
	v_rcp_f32_e32 v167, v167
	v_rcp_f32_e32 v168, v168
	v_rcp_f32_e32 v169, v169
	v_rcp_f32_e32 v170, v170
	v_rcp_f32_e32 v171, v171
	v_rcp_f32_e32 v172, v172
	v_rcp_f32_e32 v173, v173
	v_pk_mul_f32 v[166:167], v[86:87], v[166:167]
	v_pk_mul_f32 v[168:169], v[88:89], v[168:169]
	v_pk_mul_f32 v[170:171], v[82:83], v[170:171]
	v_pk_mul_f32 v[172:173], v[84:85], v[172:173]
	v_cvt_pk_bf16_f32 v178, v166, v167
	v_cvt_pk_bf16_f32 v179, v168, v169
	v_cvt_pk_bf16_f32 v180, v170, v171
	v_cvt_pk_bf16_f32 v181, v172, v173
	global_store_dwordx4 v[186:187], v[178:181], off offset:256
	v_pk_mul_f32 v[158:159], v[78:79], s[40:41]
	v_pk_mul_f32 v[160:161], v[80:81], s[40:41]
	v_pk_mul_f32 v[162:163], v[74:75], s[40:41]
	v_pk_mul_f32 v[164:165], v[76:77], s[40:41]
	v_exp_f32_e32 v158, v158
	v_exp_f32_e32 v159, v159
	v_exp_f32_e32 v160, v160
	v_exp_f32_e32 v161, v161
	v_exp_f32_e32 v162, v162
	v_exp_f32_e32 v163, v163
	v_exp_f32_e32 v164, v164
	v_exp_f32_e32 v165, v165
	v_pk_add_f32 v[158:159], v[158:159], s[42:43]
	v_pk_add_f32 v[160:161], v[160:161], s[42:43]
	v_pk_add_f32 v[162:163], v[162:163], s[42:43]
	v_pk_add_f32 v[164:165], v[164:165], s[42:43]
	v_rcp_f32_e32 v158, v158
	v_rcp_f32_e32 v159, v159
	v_rcp_f32_e32 v160, v160
	v_rcp_f32_e32 v161, v161
	v_rcp_f32_e32 v162, v162
	v_rcp_f32_e32 v163, v163
	v_rcp_f32_e32 v164, v164
	v_rcp_f32_e32 v165, v165
	v_pk_mul_f32 v[158:159], v[78:79], v[158:159]
	v_pk_mul_f32 v[160:161], v[80:81], v[160:161]
	v_pk_mul_f32 v[162:163], v[74:75], v[162:163]
	v_pk_mul_f32 v[164:165], v[76:77], v[164:165]
	v_cvt_pk_bf16_f32 v174, v158, v159
	v_cvt_pk_bf16_f32 v175, v160, v161
	v_cvt_pk_bf16_f32 v176, v162, v163
	v_cvt_pk_bf16_f32 v177, v164, v165
	global_store_dwordx4 v[188:189], v[174:177], off
	v_pk_mul_f32 v[166:167], v[70:71], s[40:41]
	v_pk_mul_f32 v[168:169], v[72:73], s[40:41]
	v_pk_mul_f32 v[170:171], v[66:67], s[40:41]
	v_pk_mul_f32 v[172:173], v[68:69], s[40:41]
	v_exp_f32_e32 v166, v166
	v_exp_f32_e32 v167, v167
	v_exp_f32_e32 v168, v168
	v_exp_f32_e32 v169, v169
	v_exp_f32_e32 v170, v170
	v_exp_f32_e32 v171, v171
	v_exp_f32_e32 v172, v172
	v_exp_f32_e32 v173, v173
	v_pk_add_f32 v[166:167], v[166:167], s[42:43]
	v_pk_add_f32 v[168:169], v[168:169], s[42:43]
	v_pk_add_f32 v[170:171], v[170:171], s[42:43]
	v_pk_add_f32 v[172:173], v[172:173], s[42:43]
	v_rcp_f32_e32 v166, v166
	v_rcp_f32_e32 v167, v167
	v_rcp_f32_e32 v168, v168
	v_rcp_f32_e32 v169, v169
	v_rcp_f32_e32 v170, v170
	v_rcp_f32_e32 v171, v171
	v_rcp_f32_e32 v172, v172
	v_rcp_f32_e32 v173, v173
	v_pk_mul_f32 v[166:167], v[70:71], v[166:167]
	v_pk_mul_f32 v[168:169], v[72:73], v[168:169]
	v_pk_mul_f32 v[170:171], v[66:67], v[170:171]
	v_pk_mul_f32 v[172:173], v[68:69], v[172:173]
	v_cvt_pk_bf16_f32 v178, v166, v167
	v_cvt_pk_bf16_f32 v179, v168, v169
	v_cvt_pk_bf16_f32 v180, v170, v171
	v_cvt_pk_bf16_f32 v181, v172, v173
	global_store_dwordx4 v[188:189], v[178:181], off offset:256
	v_pk_mul_f32 v[158:159], v[62:63], s[40:41]
	v_pk_mul_f32 v[160:161], v[64:65], s[40:41]
	v_pk_mul_f32 v[162:163], v[58:59], s[40:41]
	v_pk_mul_f32 v[164:165], v[60:61], s[40:41]
	v_exp_f32_e32 v158, v158
	v_exp_f32_e32 v159, v159
	v_exp_f32_e32 v160, v160
	v_exp_f32_e32 v161, v161
	v_exp_f32_e32 v162, v162
	v_exp_f32_e32 v163, v163
	v_exp_f32_e32 v164, v164
	v_exp_f32_e32 v165, v165
	v_pk_add_f32 v[158:159], v[158:159], s[42:43]
	v_pk_add_f32 v[160:161], v[160:161], s[42:43]
	v_pk_add_f32 v[162:163], v[162:163], s[42:43]
	v_pk_add_f32 v[164:165], v[164:165], s[42:43]
	v_rcp_f32_e32 v158, v158
	v_rcp_f32_e32 v159, v159
	v_rcp_f32_e32 v160, v160
	v_rcp_f32_e32 v161, v161
	v_rcp_f32_e32 v162, v162
	v_rcp_f32_e32 v163, v163
	v_rcp_f32_e32 v164, v164
	v_rcp_f32_e32 v165, v165
	v_pk_mul_f32 v[158:159], v[62:63], v[158:159]
	v_pk_mul_f32 v[160:161], v[64:65], v[160:161]
	v_pk_mul_f32 v[162:163], v[58:59], v[162:163]
	v_pk_mul_f32 v[164:165], v[60:61], v[164:165]
	v_cvt_pk_bf16_f32 v174, v158, v159
	v_cvt_pk_bf16_f32 v175, v160, v161
	v_cvt_pk_bf16_f32 v176, v162, v163
	v_cvt_pk_bf16_f32 v177, v164, v165
	global_store_dwordx4 v[190:191], v[174:177], off
	v_pk_mul_f32 v[166:167], v[54:55], s[40:41]
	v_pk_mul_f32 v[168:169], v[56:57], s[40:41]
	v_pk_mul_f32 v[170:171], v[50:51], s[40:41]
	v_pk_mul_f32 v[172:173], v[52:53], s[40:41]
	v_exp_f32_e32 v166, v166
	v_exp_f32_e32 v167, v167
	v_exp_f32_e32 v168, v168
	v_exp_f32_e32 v169, v169
	v_exp_f32_e32 v170, v170
	v_exp_f32_e32 v171, v171
	v_exp_f32_e32 v172, v172
	v_exp_f32_e32 v173, v173
	v_pk_add_f32 v[166:167], v[166:167], s[42:43]
	v_pk_add_f32 v[168:169], v[168:169], s[42:43]
	v_pk_add_f32 v[170:171], v[170:171], s[42:43]
	v_pk_add_f32 v[172:173], v[172:173], s[42:43]
	v_rcp_f32_e32 v166, v166
	v_rcp_f32_e32 v167, v167
	v_rcp_f32_e32 v168, v168
	v_rcp_f32_e32 v169, v169
	v_rcp_f32_e32 v170, v170
	v_rcp_f32_e32 v171, v171
	v_rcp_f32_e32 v172, v172
	v_rcp_f32_e32 v173, v173
	v_pk_mul_f32 v[166:167], v[54:55], v[166:167]
	v_pk_mul_f32 v[168:169], v[56:57], v[168:169]
	v_pk_mul_f32 v[170:171], v[50:51], v[170:171]
	v_pk_mul_f32 v[172:173], v[52:53], v[172:173]
	v_cvt_pk_bf16_f32 v178, v166, v167
	v_cvt_pk_bf16_f32 v179, v168, v169
	v_cvt_pk_bf16_f32 v180, v170, v171
	v_cvt_pk_bf16_f32 v181, v172, v173
	global_store_dwordx4 v[190:191], v[178:181], off offset:256
	v_pk_mul_f32 v[158:159], v[46:47], s[40:41]
	v_pk_mul_f32 v[160:161], v[48:49], s[40:41]
	v_pk_mul_f32 v[162:163], v[42:43], s[40:41]
	v_pk_mul_f32 v[164:165], v[44:45], s[40:41]
	v_exp_f32_e32 v158, v158
	v_exp_f32_e32 v159, v159
	v_exp_f32_e32 v160, v160
	v_exp_f32_e32 v161, v161
	v_exp_f32_e32 v162, v162
	v_exp_f32_e32 v163, v163
	v_exp_f32_e32 v164, v164
	v_exp_f32_e32 v165, v165
	v_pk_add_f32 v[158:159], v[158:159], s[42:43]
	v_pk_add_f32 v[160:161], v[160:161], s[42:43]
	v_pk_add_f32 v[162:163], v[162:163], s[42:43]
	v_pk_add_f32 v[164:165], v[164:165], s[42:43]
	v_rcp_f32_e32 v158, v158
	v_rcp_f32_e32 v159, v159
	v_rcp_f32_e32 v160, v160
	v_rcp_f32_e32 v161, v161
	v_rcp_f32_e32 v162, v162
	v_rcp_f32_e32 v163, v163
	v_rcp_f32_e32 v164, v164
	v_rcp_f32_e32 v165, v165
	v_pk_mul_f32 v[158:159], v[46:47], v[158:159]
	v_pk_mul_f32 v[160:161], v[48:49], v[160:161]
	v_pk_mul_f32 v[162:163], v[42:43], v[162:163]
	v_pk_mul_f32 v[164:165], v[44:45], v[164:165]
	v_cvt_pk_bf16_f32 v174, v158, v159
	v_cvt_pk_bf16_f32 v175, v160, v161
	v_cvt_pk_bf16_f32 v176, v162, v163
	v_cvt_pk_bf16_f32 v177, v164, v165
	global_store_dwordx4 v[192:193], v[174:177], off
	v_pk_mul_f32 v[166:167], v[38:39], s[40:41]
	v_pk_mul_f32 v[168:169], v[40:41], s[40:41]
	v_pk_mul_f32 v[170:171], v[34:35], s[40:41]
	v_pk_mul_f32 v[172:173], v[36:37], s[40:41]
	v_exp_f32_e32 v166, v166
	v_exp_f32_e32 v167, v167
	v_exp_f32_e32 v168, v168
	v_exp_f32_e32 v169, v169
	v_exp_f32_e32 v170, v170
	v_exp_f32_e32 v171, v171
	v_exp_f32_e32 v172, v172
	v_exp_f32_e32 v173, v173
	v_pk_add_f32 v[166:167], v[166:167], s[42:43]
	v_pk_add_f32 v[168:169], v[168:169], s[42:43]
	v_pk_add_f32 v[170:171], v[170:171], s[42:43]
	v_pk_add_f32 v[172:173], v[172:173], s[42:43]
	v_rcp_f32_e32 v166, v166
	v_rcp_f32_e32 v167, v167
	v_rcp_f32_e32 v168, v168
	v_rcp_f32_e32 v169, v169
	v_rcp_f32_e32 v170, v170
	v_rcp_f32_e32 v171, v171
	v_rcp_f32_e32 v172, v172
	v_rcp_f32_e32 v173, v173
	v_pk_mul_f32 v[166:167], v[38:39], v[166:167]
	v_pk_mul_f32 v[168:169], v[40:41], v[168:169]
	v_pk_mul_f32 v[170:171], v[34:35], v[170:171]
	v_pk_mul_f32 v[172:173], v[36:37], v[172:173]
	v_cvt_pk_bf16_f32 v178, v166, v167
	v_cvt_pk_bf16_f32 v179, v168, v169
	v_cvt_pk_bf16_f32 v180, v170, v171
	v_cvt_pk_bf16_f32 v181, v172, v173
	global_store_dwordx4 v[192:193], v[178:181], off offset:256
	v_pk_mul_f32 v[158:159], v[30:31], s[40:41]
	v_pk_mul_f32 v[160:161], v[32:33], s[40:41]
	v_pk_mul_f32 v[162:163], v[26:27], s[40:41]
	v_pk_mul_f32 v[164:165], v[28:29], s[40:41]
	v_exp_f32_e32 v158, v158
	v_exp_f32_e32 v159, v159
	v_exp_f32_e32 v160, v160
	v_exp_f32_e32 v161, v161
	v_exp_f32_e32 v162, v162
	v_exp_f32_e32 v163, v163
	v_exp_f32_e32 v164, v164
	v_exp_f32_e32 v165, v165
	v_pk_add_f32 v[158:159], v[158:159], s[42:43]
	v_pk_add_f32 v[160:161], v[160:161], s[42:43]
	v_pk_add_f32 v[162:163], v[162:163], s[42:43]
	v_pk_add_f32 v[164:165], v[164:165], s[42:43]
	v_rcp_f32_e32 v158, v158
	v_rcp_f32_e32 v159, v159
	v_rcp_f32_e32 v160, v160
	v_rcp_f32_e32 v161, v161
	v_rcp_f32_e32 v162, v162
	v_rcp_f32_e32 v163, v163
	v_rcp_f32_e32 v164, v164
	v_rcp_f32_e32 v165, v165
	v_pk_mul_f32 v[158:159], v[30:31], v[158:159]
	v_pk_mul_f32 v[160:161], v[32:33], v[160:161]
	v_pk_mul_f32 v[162:163], v[26:27], v[162:163]
	v_pk_mul_f32 v[164:165], v[28:29], v[164:165]
	v_cvt_pk_bf16_f32 v174, v158, v159
	v_cvt_pk_bf16_f32 v175, v160, v161
	v_cvt_pk_bf16_f32 v176, v162, v163
	v_cvt_pk_bf16_f32 v177, v164, v165
	global_store_dwordx4 v[194:195], v[174:177], off
	v_pk_mul_f32 v[166:167], v[22:23], s[40:41]
	v_pk_mul_f32 v[168:169], v[24:25], s[40:41]
	v_pk_mul_f32 v[170:171], v[18:19], s[40:41]
	v_pk_mul_f32 v[172:173], v[20:21], s[40:41]
	v_exp_f32_e32 v166, v166
	v_exp_f32_e32 v167, v167
	v_exp_f32_e32 v168, v168
	v_exp_f32_e32 v169, v169
	v_exp_f32_e32 v170, v170
	v_exp_f32_e32 v171, v171
	v_exp_f32_e32 v172, v172
	v_exp_f32_e32 v173, v173
	v_pk_add_f32 v[166:167], v[166:167], s[42:43]
	v_pk_add_f32 v[168:169], v[168:169], s[42:43]
	v_pk_add_f32 v[170:171], v[170:171], s[42:43]
	v_pk_add_f32 v[172:173], v[172:173], s[42:43]
	v_rcp_f32_e32 v166, v166
	v_rcp_f32_e32 v167, v167
	v_rcp_f32_e32 v168, v168
	v_rcp_f32_e32 v169, v169
	v_rcp_f32_e32 v170, v170
	v_rcp_f32_e32 v171, v171
	v_rcp_f32_e32 v172, v172
	v_rcp_f32_e32 v173, v173
	v_pk_mul_f32 v[166:167], v[22:23], v[166:167]
	v_pk_mul_f32 v[168:169], v[24:25], v[168:169]
	v_pk_mul_f32 v[170:171], v[18:19], v[170:171]
	v_pk_mul_f32 v[172:173], v[20:21], v[172:173]
	v_cvt_pk_bf16_f32 v178, v166, v167
	v_cvt_pk_bf16_f32 v179, v168, v169
	v_cvt_pk_bf16_f32 v180, v170, v171
	v_cvt_pk_bf16_f32 v181, v172, v173
	global_store_dwordx4 v[194:195], v[178:181], off offset:256
	v_pk_mul_f32 v[158:159], v[14:15], s[40:41]
	v_pk_mul_f32 v[160:161], v[16:17], s[40:41]
	v_pk_mul_f32 v[162:163], v[10:11], s[40:41]
	v_pk_mul_f32 v[164:165], v[12:13], s[40:41]
	v_exp_f32_e32 v158, v158
	v_exp_f32_e32 v159, v159
	v_exp_f32_e32 v160, v160
	v_exp_f32_e32 v161, v161
	v_exp_f32_e32 v162, v162
	v_exp_f32_e32 v163, v163
	v_exp_f32_e32 v164, v164
	v_exp_f32_e32 v165, v165
	v_pk_add_f32 v[158:159], v[158:159], s[42:43]
	v_pk_add_f32 v[160:161], v[160:161], s[42:43]
	v_pk_add_f32 v[162:163], v[162:163], s[42:43]
	v_pk_add_f32 v[164:165], v[164:165], s[42:43]
	v_rcp_f32_e32 v158, v158
	v_rcp_f32_e32 v159, v159
	v_rcp_f32_e32 v160, v160
	v_rcp_f32_e32 v161, v161
	v_rcp_f32_e32 v162, v162
	v_rcp_f32_e32 v163, v163
	v_rcp_f32_e32 v164, v164
	v_rcp_f32_e32 v165, v165
	v_pk_mul_f32 v[158:159], v[14:15], v[158:159]
	v_pk_mul_f32 v[160:161], v[16:17], v[160:161]
	v_pk_mul_f32 v[162:163], v[10:11], v[162:163]
	v_pk_mul_f32 v[164:165], v[12:13], v[164:165]
	v_cvt_pk_bf16_f32 v174, v158, v159
	v_cvt_pk_bf16_f32 v175, v160, v161
	v_cvt_pk_bf16_f32 v176, v162, v163
	v_cvt_pk_bf16_f32 v177, v164, v165
	global_store_dwordx4 v[196:197], v[174:177], off
	v_pk_mul_f32 v[166:167], v[6:7], s[40:41]
	v_pk_mul_f32 v[168:169], v[8:9], s[40:41]
	v_pk_mul_f32 v[170:171], v[2:3], s[40:41]
	v_pk_mul_f32 v[172:173], v[4:5], s[40:41]
	v_exp_f32_e32 v166, v166
	v_exp_f32_e32 v167, v167
	v_exp_f32_e32 v168, v168
	v_exp_f32_e32 v169, v169
	v_exp_f32_e32 v170, v170
	v_exp_f32_e32 v171, v171
	v_exp_f32_e32 v172, v172
	v_exp_f32_e32 v173, v173
	v_pk_add_f32 v[166:167], v[166:167], s[42:43]
	v_pk_add_f32 v[168:169], v[168:169], s[42:43]
	v_pk_add_f32 v[170:171], v[170:171], s[42:43]
	v_pk_add_f32 v[172:173], v[172:173], s[42:43]
	v_rcp_f32_e32 v166, v166
	v_rcp_f32_e32 v167, v167
	v_rcp_f32_e32 v168, v168
	v_rcp_f32_e32 v169, v169
	v_rcp_f32_e32 v170, v170
	v_rcp_f32_e32 v171, v171
	v_rcp_f32_e32 v172, v172
	v_rcp_f32_e32 v173, v173
	v_pk_mul_f32 v[166:167], v[6:7], v[166:167]
	v_pk_mul_f32 v[168:169], v[8:9], v[168:169]
	v_pk_mul_f32 v[170:171], v[2:3], v[170:171]
	v_pk_mul_f32 v[172:173], v[4:5], v[172:173]
	v_cvt_pk_bf16_f32 v178, v166, v167
	v_cvt_pk_bf16_f32 v179, v168, v169
	v_cvt_pk_bf16_f32 v180, v170, v171
	v_cvt_pk_bf16_f32 v181, v172, v173
	global_store_dwordx4 v[196:197], v[178:181], off offset:256
	s_branch .Lei_done
.Lei_sig:
	v_pk_mul_f32 v[158:159], v[126:127], s[40:41]
	v_pk_mul_f32 v[160:161], v[128:129], s[40:41]
	v_pk_mul_f32 v[162:163], v[122:123], s[40:41]
	v_pk_mul_f32 v[164:165], v[124:125], s[40:41]
	v_exp_f32_e32 v158, v158
	v_exp_f32_e32 v159, v159
	v_exp_f32_e32 v160, v160
	v_exp_f32_e32 v161, v161
	v_exp_f32_e32 v162, v162
	v_exp_f32_e32 v163, v163
	v_exp_f32_e32 v164, v164
	v_exp_f32_e32 v165, v165
	v_pk_add_f32 v[158:159], v[158:159], s[42:43]
	v_pk_add_f32 v[160:161], v[160:161], s[42:43]
	v_pk_add_f32 v[162:163], v[162:163], s[42:43]
	v_pk_add_f32 v[164:165], v[164:165], s[42:43]
	v_rcp_f32_e32 v158, v158
	v_rcp_f32_e32 v159, v159
	v_rcp_f32_e32 v160, v160
	v_rcp_f32_e32 v161, v161
	v_rcp_f32_e32 v162, v162
	v_rcp_f32_e32 v163, v163
	v_rcp_f32_e32 v164, v164
	v_rcp_f32_e32 v165, v165
	v_cvt_pk_bf16_f32 v174, v158, v159
	v_cvt_pk_bf16_f32 v175, v160, v161
	v_cvt_pk_bf16_f32 v176, v162, v163
	v_cvt_pk_bf16_f32 v177, v164, v165
	global_store_dwordx4 v[182:183], v[174:177], off
	v_pk_mul_f32 v[166:167], v[118:119], s[40:41]
	v_pk_mul_f32 v[168:169], v[120:121], s[40:41]
	v_pk_mul_f32 v[170:171], v[114:115], s[40:41]
	v_pk_mul_f32 v[172:173], v[116:117], s[40:41]
	v_exp_f32_e32 v166, v166
	v_exp_f32_e32 v167, v167
	v_exp_f32_e32 v168, v168
	v_exp_f32_e32 v169, v169
	v_exp_f32_e32 v170, v170
	v_exp_f32_e32 v171, v171
	v_exp_f32_e32 v172, v172
	v_exp_f32_e32 v173, v173
	v_pk_add_f32 v[166:167], v[166:167], s[42:43]
	v_pk_add_f32 v[168:169], v[168:169], s[42:43]
	v_pk_add_f32 v[170:171], v[170:171], s[42:43]
	v_pk_add_f32 v[172:173], v[172:173], s[42:43]
	v_rcp_f32_e32 v166, v166
	v_rcp_f32_e32 v167, v167
	v_rcp_f32_e32 v168, v168
	v_rcp_f32_e32 v169, v169
	v_rcp_f32_e32 v170, v170
	v_rcp_f32_e32 v171, v171
	v_rcp_f32_e32 v172, v172
	v_rcp_f32_e32 v173, v173
	v_cvt_pk_bf16_f32 v178, v166, v167
	v_cvt_pk_bf16_f32 v179, v168, v169
	v_cvt_pk_bf16_f32 v180, v170, v171
	v_cvt_pk_bf16_f32 v181, v172, v173
	global_store_dwordx4 v[182:183], v[178:181], off offset:256
	v_pk_mul_f32 v[158:159], v[110:111], s[40:41]
	v_pk_mul_f32 v[160:161], v[112:113], s[40:41]
	v_pk_mul_f32 v[162:163], v[106:107], s[40:41]
	v_pk_mul_f32 v[164:165], v[108:109], s[40:41]
	v_exp_f32_e32 v158, v158
	v_exp_f32_e32 v159, v159
	v_exp_f32_e32 v160, v160
	v_exp_f32_e32 v161, v161
	v_exp_f32_e32 v162, v162
	v_exp_f32_e32 v163, v163
	v_exp_f32_e32 v164, v164
	v_exp_f32_e32 v165, v165
	v_pk_add_f32 v[158:159], v[158:159], s[42:43]
	v_pk_add_f32 v[160:161], v[160:161], s[42:43]
	v_pk_add_f32 v[162:163], v[162:163], s[42:43]
	v_pk_add_f32 v[164:165], v[164:165], s[42:43]
	v_rcp_f32_e32 v158, v158
	v_rcp_f32_e32 v159, v159
	v_rcp_f32_e32 v160, v160
	v_rcp_f32_e32 v161, v161
	v_rcp_f32_e32 v162, v162
	v_rcp_f32_e32 v163, v163
	v_rcp_f32_e32 v164, v164
	v_rcp_f32_e32 v165, v165
	v_cvt_pk_bf16_f32 v174, v158, v159
	v_cvt_pk_bf16_f32 v175, v160, v161
	v_cvt_pk_bf16_f32 v176, v162, v163
	v_cvt_pk_bf16_f32 v177, v164, v165
	global_store_dwordx4 v[184:185], v[174:177], off
	v_pk_mul_f32 v[166:167], v[102:103], s[40:41]
	v_pk_mul_f32 v[168:169], v[104:105], s[40:41]
	v_pk_mul_f32 v[170:171], v[98:99], s[40:41]
	v_pk_mul_f32 v[172:173], v[100:101], s[40:41]
	v_exp_f32_e32 v166, v166
	v_exp_f32_e32 v167, v167
	v_exp_f32_e32 v168, v168
	v_exp_f32_e32 v169, v169
	v_exp_f32_e32 v170, v170
	v_exp_f32_e32 v171, v171
	v_exp_f32_e32 v172, v172
	v_exp_f32_e32 v173, v173
	v_pk_add_f32 v[166:167], v[166:167], s[42:43]
	v_pk_add_f32 v[168:169], v[168:169], s[42:43]
	v_pk_add_f32 v[170:171], v[170:171], s[42:43]
	v_pk_add_f32 v[172:173], v[172:173], s[42:43]
	v_rcp_f32_e32 v166, v166
	v_rcp_f32_e32 v167, v167
	v_rcp_f32_e32 v168, v168
	v_rcp_f32_e32 v169, v169
	v_rcp_f32_e32 v170, v170
	v_rcp_f32_e32 v171, v171
	v_rcp_f32_e32 v172, v172
	v_rcp_f32_e32 v173, v173
	v_cvt_pk_bf16_f32 v178, v166, v167
	v_cvt_pk_bf16_f32 v179, v168, v169
	v_cvt_pk_bf16_f32 v180, v170, v171
	v_cvt_pk_bf16_f32 v181, v172, v173
	global_store_dwordx4 v[184:185], v[178:181], off offset:256
	v_pk_mul_f32 v[158:159], v[94:95], s[40:41]
	v_pk_mul_f32 v[160:161], v[96:97], s[40:41]
	v_pk_mul_f32 v[162:163], v[90:91], s[40:41]
	v_pk_mul_f32 v[164:165], v[92:93], s[40:41]
	v_exp_f32_e32 v158, v158
	v_exp_f32_e32 v159, v159
	v_exp_f32_e32 v160, v160
	v_exp_f32_e32 v161, v161
	v_exp_f32_e32 v162, v162
	v_exp_f32_e32 v163, v163
	v_exp_f32_e32 v164, v164
	v_exp_f32_e32 v165, v165
	v_pk_add_f32 v[158:159], v[158:159], s[42:43]
	v_pk_add_f32 v[160:161], v[160:161], s[42:43]
	v_pk_add_f32 v[162:163], v[162:163], s[42:43]
	v_pk_add_f32 v[164:165], v[164:165], s[42:43]
	v_rcp_f32_e32 v158, v158
	v_rcp_f32_e32 v159, v159
	v_rcp_f32_e32 v160, v160
	v_rcp_f32_e32 v161, v161
	v_rcp_f32_e32 v162, v162
	v_rcp_f32_e32 v163, v163
	v_rcp_f32_e32 v164, v164
	v_rcp_f32_e32 v165, v165
	v_cvt_pk_bf16_f32 v174, v158, v159
	v_cvt_pk_bf16_f32 v175, v160, v161
	v_cvt_pk_bf16_f32 v176, v162, v163
	v_cvt_pk_bf16_f32 v177, v164, v165
	global_store_dwordx4 v[186:187], v[174:177], off
	v_pk_mul_f32 v[166:167], v[86:87], s[40:41]
	v_pk_mul_f32 v[168:169], v[88:89], s[40:41]
	v_pk_mul_f32 v[170:171], v[82:83], s[40:41]
	v_pk_mul_f32 v[172:173], v[84:85], s[40:41]
	v_exp_f32_e32 v166, v166
	v_exp_f32_e32 v167, v167
	v_exp_f32_e32 v168, v168
	v_exp_f32_e32 v169, v169
	v_exp_f32_e32 v170, v170
	v_exp_f32_e32 v171, v171
	v_exp_f32_e32 v172, v172
	v_exp_f32_e32 v173, v173
	v_pk_add_f32 v[166:167], v[166:167], s[42:43]
	v_pk_add_f32 v[168:169], v[168:169], s[42:43]
	v_pk_add_f32 v[170:171], v[170:171], s[42:43]
	v_pk_add_f32 v[172:173], v[172:173], s[42:43]
	v_rcp_f32_e32 v166, v166
	v_rcp_f32_e32 v167, v167
	v_rcp_f32_e32 v168, v168
	v_rcp_f32_e32 v169, v169
	v_rcp_f32_e32 v170, v170
	v_rcp_f32_e32 v171, v171
	v_rcp_f32_e32 v172, v172
	v_rcp_f32_e32 v173, v173
	v_cvt_pk_bf16_f32 v178, v166, v167
	v_cvt_pk_bf16_f32 v179, v168, v169
	v_cvt_pk_bf16_f32 v180, v170, v171
	v_cvt_pk_bf16_f32 v181, v172, v173
	global_store_dwordx4 v[186:187], v[178:181], off offset:256
	v_pk_mul_f32 v[158:159], v[78:79], s[40:41]
	v_pk_mul_f32 v[160:161], v[80:81], s[40:41]
	v_pk_mul_f32 v[162:163], v[74:75], s[40:41]
	v_pk_mul_f32 v[164:165], v[76:77], s[40:41]
	v_exp_f32_e32 v158, v158
	v_exp_f32_e32 v159, v159
	v_exp_f32_e32 v160, v160
	v_exp_f32_e32 v161, v161
	v_exp_f32_e32 v162, v162
	v_exp_f32_e32 v163, v163
	v_exp_f32_e32 v164, v164
	v_exp_f32_e32 v165, v165
	v_pk_add_f32 v[158:159], v[158:159], s[42:43]
	v_pk_add_f32 v[160:161], v[160:161], s[42:43]
	v_pk_add_f32 v[162:163], v[162:163], s[42:43]
	v_pk_add_f32 v[164:165], v[164:165], s[42:43]
	v_rcp_f32_e32 v158, v158
	v_rcp_f32_e32 v159, v159
	v_rcp_f32_e32 v160, v160
	v_rcp_f32_e32 v161, v161
	v_rcp_f32_e32 v162, v162
	v_rcp_f32_e32 v163, v163
	v_rcp_f32_e32 v164, v164
	v_rcp_f32_e32 v165, v165
	v_cvt_pk_bf16_f32 v174, v158, v159
	v_cvt_pk_bf16_f32 v175, v160, v161
	v_cvt_pk_bf16_f32 v176, v162, v163
	v_cvt_pk_bf16_f32 v177, v164, v165
	global_store_dwordx4 v[188:189], v[174:177], off
	v_pk_mul_f32 v[166:167], v[70:71], s[40:41]
	v_pk_mul_f32 v[168:169], v[72:73], s[40:41]
	v_pk_mul_f32 v[170:171], v[66:67], s[40:41]
	v_pk_mul_f32 v[172:173], v[68:69], s[40:41]
	v_exp_f32_e32 v166, v166
	v_exp_f32_e32 v167, v167
	v_exp_f32_e32 v168, v168
	v_exp_f32_e32 v169, v169
	v_exp_f32_e32 v170, v170
	v_exp_f32_e32 v171, v171
	v_exp_f32_e32 v172, v172
	v_exp_f32_e32 v173, v173
	v_pk_add_f32 v[166:167], v[166:167], s[42:43]
	v_pk_add_f32 v[168:169], v[168:169], s[42:43]
	v_pk_add_f32 v[170:171], v[170:171], s[42:43]
	v_pk_add_f32 v[172:173], v[172:173], s[42:43]
	v_rcp_f32_e32 v166, v166
	v_rcp_f32_e32 v167, v167
	v_rcp_f32_e32 v168, v168
	v_rcp_f32_e32 v169, v169
	v_rcp_f32_e32 v170, v170
	v_rcp_f32_e32 v171, v171
	v_rcp_f32_e32 v172, v172
	v_rcp_f32_e32 v173, v173
	v_cvt_pk_bf16_f32 v178, v166, v167
	v_cvt_pk_bf16_f32 v179, v168, v169
	v_cvt_pk_bf16_f32 v180, v170, v171
	v_cvt_pk_bf16_f32 v181, v172, v173
	global_store_dwordx4 v[188:189], v[178:181], off offset:256
	v_pk_mul_f32 v[158:159], v[62:63], s[40:41]
	v_pk_mul_f32 v[160:161], v[64:65], s[40:41]
	v_pk_mul_f32 v[162:163], v[58:59], s[40:41]
	v_pk_mul_f32 v[164:165], v[60:61], s[40:41]
	v_exp_f32_e32 v158, v158
	v_exp_f32_e32 v159, v159
	v_exp_f32_e32 v160, v160
	v_exp_f32_e32 v161, v161
	v_exp_f32_e32 v162, v162
	v_exp_f32_e32 v163, v163
	v_exp_f32_e32 v164, v164
	v_exp_f32_e32 v165, v165
	v_pk_add_f32 v[158:159], v[158:159], s[42:43]
	v_pk_add_f32 v[160:161], v[160:161], s[42:43]
	v_pk_add_f32 v[162:163], v[162:163], s[42:43]
	v_pk_add_f32 v[164:165], v[164:165], s[42:43]
	v_rcp_f32_e32 v158, v158
	v_rcp_f32_e32 v159, v159
	v_rcp_f32_e32 v160, v160
	v_rcp_f32_e32 v161, v161
	v_rcp_f32_e32 v162, v162
	v_rcp_f32_e32 v163, v163
	v_rcp_f32_e32 v164, v164
	v_rcp_f32_e32 v165, v165
	v_cvt_pk_bf16_f32 v174, v158, v159
	v_cvt_pk_bf16_f32 v175, v160, v161
	v_cvt_pk_bf16_f32 v176, v162, v163
	v_cvt_pk_bf16_f32 v177, v164, v165
	global_store_dwordx4 v[190:191], v[174:177], off
	v_pk_mul_f32 v[166:167], v[54:55], s[40:41]
	v_pk_mul_f32 v[168:169], v[56:57], s[40:41]
	v_pk_mul_f32 v[170:171], v[50:51], s[40:41]
	v_pk_mul_f32 v[172:173], v[52:53], s[40:41]
	v_exp_f32_e32 v166, v166
	v_exp_f32_e32 v167, v167
	v_exp_f32_e32 v168, v168
	v_exp_f32_e32 v169, v169
	v_exp_f32_e32 v170, v170
	v_exp_f32_e32 v171, v171
	v_exp_f32_e32 v172, v172
	v_exp_f32_e32 v173, v173
	v_pk_add_f32 v[166:167], v[166:167], s[42:43]
	v_pk_add_f32 v[168:169], v[168:169], s[42:43]
	v_pk_add_f32 v[170:171], v[170:171], s[42:43]
	v_pk_add_f32 v[172:173], v[172:173], s[42:43]
	v_rcp_f32_e32 v166, v166
	v_rcp_f32_e32 v167, v167
	v_rcp_f32_e32 v168, v168
	v_rcp_f32_e32 v169, v169
	v_rcp_f32_e32 v170, v170
	v_rcp_f32_e32 v171, v171
	v_rcp_f32_e32 v172, v172
	v_rcp_f32_e32 v173, v173
	v_cvt_pk_bf16_f32 v178, v166, v167
	v_cvt_pk_bf16_f32 v179, v168, v169
	v_cvt_pk_bf16_f32 v180, v170, v171
	v_cvt_pk_bf16_f32 v181, v172, v173
	global_store_dwordx4 v[190:191], v[178:181], off offset:256
	v_pk_mul_f32 v[158:159], v[46:47], s[40:41]
	v_pk_mul_f32 v[160:161], v[48:49], s[40:41]
	v_pk_mul_f32 v[162:163], v[42:43], s[40:41]
	v_pk_mul_f32 v[164:165], v[44:45], s[40:41]
	v_exp_f32_e32 v158, v158
	v_exp_f32_e32 v159, v159
	v_exp_f32_e32 v160, v160
	v_exp_f32_e32 v161, v161
	v_exp_f32_e32 v162, v162
	v_exp_f32_e32 v163, v163
	v_exp_f32_e32 v164, v164
	v_exp_f32_e32 v165, v165
	v_pk_add_f32 v[158:159], v[158:159], s[42:43]
	v_pk_add_f32 v[160:161], v[160:161], s[42:43]
	v_pk_add_f32 v[162:163], v[162:163], s[42:43]
	v_pk_add_f32 v[164:165], v[164:165], s[42:43]
	v_rcp_f32_e32 v158, v158
	v_rcp_f32_e32 v159, v159
	v_rcp_f32_e32 v160, v160
	v_rcp_f32_e32 v161, v161
	v_rcp_f32_e32 v162, v162
	v_rcp_f32_e32 v163, v163
	v_rcp_f32_e32 v164, v164
	v_rcp_f32_e32 v165, v165
	v_cvt_pk_bf16_f32 v174, v158, v159
	v_cvt_pk_bf16_f32 v175, v160, v161
	v_cvt_pk_bf16_f32 v176, v162, v163
	v_cvt_pk_bf16_f32 v177, v164, v165
	global_store_dwordx4 v[192:193], v[174:177], off
	v_pk_mul_f32 v[166:167], v[38:39], s[40:41]
	v_pk_mul_f32 v[168:169], v[40:41], s[40:41]
	v_pk_mul_f32 v[170:171], v[34:35], s[40:41]
	v_pk_mul_f32 v[172:173], v[36:37], s[40:41]
	v_exp_f32_e32 v166, v166
	v_exp_f32_e32 v167, v167
	v_exp_f32_e32 v168, v168
	v_exp_f32_e32 v169, v169
	v_exp_f32_e32 v170, v170
	v_exp_f32_e32 v171, v171
	v_exp_f32_e32 v172, v172
	v_exp_f32_e32 v173, v173
	v_pk_add_f32 v[166:167], v[166:167], s[42:43]
	v_pk_add_f32 v[168:169], v[168:169], s[42:43]
	v_pk_add_f32 v[170:171], v[170:171], s[42:43]
	v_pk_add_f32 v[172:173], v[172:173], s[42:43]
	v_rcp_f32_e32 v166, v166
	v_rcp_f32_e32 v167, v167
	v_rcp_f32_e32 v168, v168
	v_rcp_f32_e32 v169, v169
	v_rcp_f32_e32 v170, v170
	v_rcp_f32_e32 v171, v171
	v_rcp_f32_e32 v172, v172
	v_rcp_f32_e32 v173, v173
	v_cvt_pk_bf16_f32 v178, v166, v167
	v_cvt_pk_bf16_f32 v179, v168, v169
	v_cvt_pk_bf16_f32 v180, v170, v171
	v_cvt_pk_bf16_f32 v181, v172, v173
	global_store_dwordx4 v[192:193], v[178:181], off offset:256
	v_pk_mul_f32 v[158:159], v[30:31], s[40:41]
	v_pk_mul_f32 v[160:161], v[32:33], s[40:41]
	v_pk_mul_f32 v[162:163], v[26:27], s[40:41]
	v_pk_mul_f32 v[164:165], v[28:29], s[40:41]
	v_exp_f32_e32 v158, v158
	v_exp_f32_e32 v159, v159
	v_exp_f32_e32 v160, v160
	v_exp_f32_e32 v161, v161
	v_exp_f32_e32 v162, v162
	v_exp_f32_e32 v163, v163
	v_exp_f32_e32 v164, v164
	v_exp_f32_e32 v165, v165
	v_pk_add_f32 v[158:159], v[158:159], s[42:43]
	v_pk_add_f32 v[160:161], v[160:161], s[42:43]
	v_pk_add_f32 v[162:163], v[162:163], s[42:43]
	v_pk_add_f32 v[164:165], v[164:165], s[42:43]
	v_rcp_f32_e32 v158, v158
	v_rcp_f32_e32 v159, v159
	v_rcp_f32_e32 v160, v160
	v_rcp_f32_e32 v161, v161
	v_rcp_f32_e32 v162, v162
	v_rcp_f32_e32 v163, v163
	v_rcp_f32_e32 v164, v164
	v_rcp_f32_e32 v165, v165
	v_cvt_pk_bf16_f32 v174, v158, v159
	v_cvt_pk_bf16_f32 v175, v160, v161
	v_cvt_pk_bf16_f32 v176, v162, v163
	v_cvt_pk_bf16_f32 v177, v164, v165
	global_store_dwordx4 v[194:195], v[174:177], off
	v_pk_mul_f32 v[166:167], v[22:23], s[40:41]
	v_pk_mul_f32 v[168:169], v[24:25], s[40:41]
	v_pk_mul_f32 v[170:171], v[18:19], s[40:41]
	v_pk_mul_f32 v[172:173], v[20:21], s[40:41]
	v_exp_f32_e32 v166, v166
	v_exp_f32_e32 v167, v167
	v_exp_f32_e32 v168, v168
	v_exp_f32_e32 v169, v169
	v_exp_f32_e32 v170, v170
	v_exp_f32_e32 v171, v171
	v_exp_f32_e32 v172, v172
	v_exp_f32_e32 v173, v173
	v_pk_add_f32 v[166:167], v[166:167], s[42:43]
	v_pk_add_f32 v[168:169], v[168:169], s[42:43]
	v_pk_add_f32 v[170:171], v[170:171], s[42:43]
	v_pk_add_f32 v[172:173], v[172:173], s[42:43]
	v_rcp_f32_e32 v166, v166
	v_rcp_f32_e32 v167, v167
	v_rcp_f32_e32 v168, v168
	v_rcp_f32_e32 v169, v169
	v_rcp_f32_e32 v170, v170
	v_rcp_f32_e32 v171, v171
	v_rcp_f32_e32 v172, v172
	v_rcp_f32_e32 v173, v173
	v_cvt_pk_bf16_f32 v178, v166, v167
	v_cvt_pk_bf16_f32 v179, v168, v169
	v_cvt_pk_bf16_f32 v180, v170, v171
	v_cvt_pk_bf16_f32 v181, v172, v173
	global_store_dwordx4 v[194:195], v[178:181], off offset:256
	v_pk_mul_f32 v[158:159], v[14:15], s[40:41]
	v_pk_mul_f32 v[160:161], v[16:17], s[40:41]
	v_pk_mul_f32 v[162:163], v[10:11], s[40:41]
	v_pk_mul_f32 v[164:165], v[12:13], s[40:41]
	v_exp_f32_e32 v158, v158
	v_exp_f32_e32 v159, v159
	v_exp_f32_e32 v160, v160
	v_exp_f32_e32 v161, v161
	v_exp_f32_e32 v162, v162
	v_exp_f32_e32 v163, v163
	v_exp_f32_e32 v164, v164
	v_exp_f32_e32 v165, v165
	v_pk_add_f32 v[158:159], v[158:159], s[42:43]
	v_pk_add_f32 v[160:161], v[160:161], s[42:43]
	v_pk_add_f32 v[162:163], v[162:163], s[42:43]
	v_pk_add_f32 v[164:165], v[164:165], s[42:43]
	v_rcp_f32_e32 v158, v158
	v_rcp_f32_e32 v159, v159
	v_rcp_f32_e32 v160, v160
	v_rcp_f32_e32 v161, v161
	v_rcp_f32_e32 v162, v162
	v_rcp_f32_e32 v163, v163
	v_rcp_f32_e32 v164, v164
	v_rcp_f32_e32 v165, v165
	v_cvt_pk_bf16_f32 v174, v158, v159
	v_cvt_pk_bf16_f32 v175, v160, v161
	v_cvt_pk_bf16_f32 v176, v162, v163
	v_cvt_pk_bf16_f32 v177, v164, v165
	global_store_dwordx4 v[196:197], v[174:177], off
	v_pk_mul_f32 v[166:167], v[6:7], s[40:41]
	v_pk_mul_f32 v[168:169], v[8:9], s[40:41]
	v_pk_mul_f32 v[170:171], v[2:3], s[40:41]
	v_pk_mul_f32 v[172:173], v[4:5], s[40:41]
	v_exp_f32_e32 v166, v166
	v_exp_f32_e32 v167, v167
	v_exp_f32_e32 v168, v168
	v_exp_f32_e32 v169, v169
	v_exp_f32_e32 v170, v170
	v_exp_f32_e32 v171, v171
	v_exp_f32_e32 v172, v172
	v_exp_f32_e32 v173, v173
	v_pk_add_f32 v[166:167], v[166:167], s[42:43]
	v_pk_add_f32 v[168:169], v[168:169], s[42:43]
	v_pk_add_f32 v[170:171], v[170:171], s[42:43]
	v_pk_add_f32 v[172:173], v[172:173], s[42:43]
	v_rcp_f32_e32 v166, v166
	v_rcp_f32_e32 v167, v167
	v_rcp_f32_e32 v168, v168
	v_rcp_f32_e32 v169, v169
	v_rcp_f32_e32 v170, v170
	v_rcp_f32_e32 v171, v171
	v_rcp_f32_e32 v172, v172
	v_rcp_f32_e32 v173, v173
	v_cvt_pk_bf16_f32 v178, v166, v167
	v_cvt_pk_bf16_f32 v179, v168, v169
	v_cvt_pk_bf16_f32 v180, v170, v171
	v_cvt_pk_bf16_f32 v181, v172, v173
	global_store_dwordx4 v[196:197], v[178:181], off offset:256
	s_branch .Lei_done
.Lei_plain:
	v_cvt_pk_bf16_f32 v174, v126, v127
	v_cvt_pk_bf16_f32 v175, v128, v129
	v_cvt_pk_bf16_f32 v176, v122, v123
	v_cvt_pk_bf16_f32 v177, v124, v125
	global_store_dwordx4 v[182:183], v[174:177], off
	v_cvt_pk_bf16_f32 v178, v118, v119
	v_cvt_pk_bf16_f32 v179, v120, v121
	v_cvt_pk_bf16_f32 v180, v114, v115
	v_cvt_pk_bf16_f32 v181, v116, v117
	global_store_dwordx4 v[182:183], v[178:181], off offset:256
	v_cvt_pk_bf16_f32 v174, v110, v111
	v_cvt_pk_bf16_f32 v175, v112, v113
	v_cvt_pk_bf16_f32 v176, v106, v107
	v_cvt_pk_bf16_f32 v177, v108, v109
	global_store_dwordx4 v[184:185], v[174:177], off
	v_cvt_pk_bf16_f32 v178, v102, v103
	v_cvt_pk_bf16_f32 v179, v104, v105
	v_cvt_pk_bf16_f32 v180, v98, v99
	v_cvt_pk_bf16_f32 v181, v100, v101
	global_store_dwordx4 v[184:185], v[178:181], off offset:256
	v_cvt_pk_bf16_f32 v174, v94, v95
	v_cvt_pk_bf16_f32 v175, v96, v97
	v_cvt_pk_bf16_f32 v176, v90, v91
	v_cvt_pk_bf16_f32 v177, v92, v93
	global_store_dwordx4 v[186:187], v[174:177], off
	v_cvt_pk_bf16_f32 v178, v86, v87
	v_cvt_pk_bf16_f32 v179, v88, v89
	v_cvt_pk_bf16_f32 v180, v82, v83
	v_cvt_pk_bf16_f32 v181, v84, v85
	global_store_dwordx4 v[186:187], v[178:181], off offset:256
	v_cvt_pk_bf16_f32 v174, v78, v79
	v_cvt_pk_bf16_f32 v175, v80, v81
	v_cvt_pk_bf16_f32 v176, v74, v75
	v_cvt_pk_bf16_f32 v177, v76, v77
	global_store_dwordx4 v[188:189], v[174:177], off
	v_cvt_pk_bf16_f32 v178, v70, v71
	v_cvt_pk_bf16_f32 v179, v72, v73
	v_cvt_pk_bf16_f32 v180, v66, v67
	v_cvt_pk_bf16_f32 v181, v68, v69
	global_store_dwordx4 v[188:189], v[178:181], off offset:256
	v_cvt_pk_bf16_f32 v174, v62, v63
	v_cvt_pk_bf16_f32 v175, v64, v65
	v_cvt_pk_bf16_f32 v176, v58, v59
	v_cvt_pk_bf16_f32 v177, v60, v61
	global_store_dwordx4 v[190:191], v[174:177], off
	v_cvt_pk_bf16_f32 v178, v54, v55
	v_cvt_pk_bf16_f32 v179, v56, v57
	v_cvt_pk_bf16_f32 v180, v50, v51
	v_cvt_pk_bf16_f32 v181, v52, v53
	global_store_dwordx4 v[190:191], v[178:181], off offset:256
	v_cvt_pk_bf16_f32 v174, v46, v47
	v_cvt_pk_bf16_f32 v175, v48, v49
	v_cvt_pk_bf16_f32 v176, v42, v43
	v_cvt_pk_bf16_f32 v177, v44, v45
	global_store_dwordx4 v[192:193], v[174:177], off
	v_cvt_pk_bf16_f32 v178, v38, v39
	v_cvt_pk_bf16_f32 v179, v40, v41
	v_cvt_pk_bf16_f32 v180, v34, v35
	v_cvt_pk_bf16_f32 v181, v36, v37
	global_store_dwordx4 v[192:193], v[178:181], off offset:256
	v_cvt_pk_bf16_f32 v174, v30, v31
	v_cvt_pk_bf16_f32 v175, v32, v33
	v_cvt_pk_bf16_f32 v176, v26, v27
	v_cvt_pk_bf16_f32 v177, v28, v29
	global_store_dwordx4 v[194:195], v[174:177], off
	v_cvt_pk_bf16_f32 v178, v22, v23
	v_cvt_pk_bf16_f32 v179, v24, v25
	v_cvt_pk_bf16_f32 v180, v18, v19
	v_cvt_pk_bf16_f32 v181, v20, v21
	global_store_dwordx4 v[194:195], v[178:181], off offset:256
	v_cvt_pk_bf16_f32 v174, v14, v15
	v_cvt_pk_bf16_f32 v175, v16, v17
	v_cvt_pk_bf16_f32 v176, v10, v11
	v_cvt_pk_bf16_f32 v177, v12, v13
	global_store_dwordx4 v[196:197], v[174:177], off
	v_cvt_pk_bf16_f32 v178, v6, v7
	v_cvt_pk_bf16_f32 v179, v8, v9
	v_cvt_pk_bf16_f32 v180, v2, v3
	v_cvt_pk_bf16_f32 v181, v4, v5
	global_store_dwordx4 v[196:197], v[178:181], off offset:256
.Lei_done:
	s_andn2_b64 vcc, exec, s[56:57]
	s_mov_b64 s[10:11], -1
	s_cbranch_vccnz .LBB0_252
	s_andn2_b64 vcc, exec, s[44:45]
	s_cbranch_vccnz .LBB0_251
	s_barrier
	s_branch .LBB0_251

.LBB0_488:
	s_or_b64 exec, exec, s[10:11]
	v_mov_b32_e32 v1, s16
	s_waitcnt lgkmcnt(0)
	s_barrier
	ds_read_b32 v1, v1
	s_mov_b64 s[44:45], s[0:1]
	s_mov_b64 s[10:11], -1
	s_waitcnt lgkmcnt(0)
	v_cmp_le_i32_e32 vcc, s34, v1
	v_readfirstlane_b32 s62, v1
	s_cbranch_vccnz .LBB0_483
	s_cmp_gt_i32 s62, 63
	s_cbranch_scc0 .LBB0_777
	v_readlane_b32 s6, v255, 24
	s_cmp_ge_i32 s62, s6
	s_cbranch_scc0 .LBB0_764
	v_readlane_b32 s6, v255, 25
	s_cmp_ge_i32 s62, s6
	s_cbranch_scc0 .LBB0_753
	v_readlane_b32 s6, v255, 26
	s_cmp_lt_i32 s62, s6
	s_cbranch_scc1 .LBB0_500
	v_readlane_b32 s6, v255, 31
	s_cmp_ge_i32 s62, s6
	v_readlane_b32 s6, v255, 29
	s_cselect_b64 s[10:11], -1, 0
	s_cmp_lt_i32 s62, s6
	s_cselect_b64 s[14:15], -1, 0
	s_and_b64 s[10:11], s[10:11], s[14:15]
	s_andn2_b64 vcc, exec, s[10:11]
	s_mov_b64 s[10:11], -1
	s_cbranch_vccz .LBB0_738
	v_readlane_b32 s6, v255, 27
	s_cmp_ge_i32 s62, s6
	s_cbranch_scc0 .LBB0_718
	v_readlane_b32 s6, v255, 28
	s_cmp_ge_i32 s62, s6
	s_cbranch_scc0 .LBB0_554
	v_readlane_b32 s6, v255, 31
	s_cmp_ge_i32 s62, s6
	s_cbranch_scc0 .LBB0_531
	v_readlane_b32 s6, v255, 30
	s_cmp_ge_i32 s62, s6
	s_cbranch_scc1 .LBB0_520
	s_and_saveexec_b64 s[10:11], s[4:5]
	s_cbranch_execz .LBB0_509
	s_mov_b32 s6, 0x4000001
	s_branch .LBB0_502

.LBB0_509:
	s_or_b64 exec, exec, s[10:11]
	v_mov_b32_e32 v1, v232
	s_barrier
	s_load_dwordx2 s[14:15], s[44:45], 0xb0
	s_mov_b32 s27, 0xffffe0
	s_waitcnt vmcnt(0)
	v_bfe_i32 v4, v1, 27, 1
	v_lshlrev_b32_e32 v2, 4, v1
	v_lshrrev_b32_e32 v4, 22, v4
	v_add_u32_e32 v4, v2, v4
	v_and_b32_e32 v4, 0xfffffc00, v4
	v_sub_u32_e32 v4, v2, v4
	v_ashrrev_i32_e32 v3, 31, v1
	v_lshrrev_b32_e32 v5, 4, v4
	v_lshrrev_b32_e32 v3, 26, v3
	v_bitop3_b32 v5, v5, v4, 32 bitop3:0x6c
	v_ashrrev_i32_e32 v4, 31, v4
	v_add_u32_e32 v3, v1, v3
	v_lshrrev_b32_e32 v4, 26, v4
	v_ashrrev_i32_e32 v3, 6, v3
	v_add_u32_e32 v4, v5, v4
	v_lshlrev_b32_e32 v6, 3, v3
	v_ashrrev_i32_e32 v4, 6, v4
	v_and_b32_e32 v6, -16, v6
	v_mul_i32_i24_e32 v7, 64, v4
	v_add_u32_e32 v6, v4, v6
	v_sub_u32_e32 v5, v5, v7
	v_lshlrev_b32_e32 v3, 5, v3
	v_ashrrev_i16_sdwa v5, v233, sext(v5) dst_sel:DWORD dst_unused:UNUSED_PAD src0_sel:DWORD src1_sel:BYTE_0
	v_lshlrev_b32_e32 v7, 1, v6
	v_lshrrev_b32_e32 v8, 2, v6
	v_and_b32_e32 v4, 3, v4
	v_and_b32_e32 v3, 32, v3
	v_bfe_i32 v5, v5, 0, 16
	v_and_b32_e32 v7, 24, v7
	v_and_b32_e32 v8, 4, v8
	v_and_or_b32 v4, v6, s27, v4
	v_or3_b32 v4, v4, v8, v7
	v_add_lshl_u32 v3, v3, v5, 1
	v_add_u32_e32 v2, 0x2000, v2
	v_lshl_add_u32 v66, v6, 8, v3
	v_lshl_add_u32 v68, v4, 8, v3
	v_ashrrev_i32_e32 v3, 31, v2
	v_lshrrev_b32_e32 v3, 22, v3
	v_add_u32_e32 v3, v2, v3
	v_ashrrev_i32_e32 v3, 10, v3
	v_mul_i32_i24_e32 v4, 0x400, v3
	v_sub_u32_e32 v2, v2, v4
	v_lshrrev_b32_e32 v4, 4, v2
	v_readlane_b32 s6, v255, 29
	v_bitop3_b32 v2, v4, v2, 32 bitop3:0x6c
	s_sub_i32 s6, s62, s6
	v_ashrrev_i32_e32 v5, 31, v2
	s_waitcnt lgkmcnt(0)
	s_add_u32 s10, s14, 0xdc000
	v_lshrrev_b32_e32 v5, 26, v5
	s_addc_u32 s11, s15, 0
	v_lshlrev_b32_e32 v4, 3, v3
	v_add_u32_e32 v5, v2, v5
	s_add_u32 s18, s14, 0x100000
	v_and_b32_e32 v4, -16, v4
	v_ashrrev_i32_e32 v6, 6, v5
	s_addc_u32 s30, s15, 0
	s_lshl_b32 s26, s6, 2
	v_readfirstlane_b32 s6, v1
	v_add_u32_e32 v4, v6, v4
	v_and_b32_e32 v6, 3, v6
	v_and_b32_e32 v5, 0xc0, v5
	v_and_or_b32 v6, v4, s27, v6
	s_ashr_i32 s48, s6, 6
	s_ashr_i32 s27, s26, 31
	s_ashr_i32 s42, s6, 8
	v_sub_u32_e32 v2, v2, v5
	s_lshl_b64 s[36:37], s[26:27], 16
	s_lshl_b32 s27, s48, 10
	v_lshlrev_b32_e32 v3, 5, v3
	v_ashrrev_i16_sdwa v2, v233, sext(v2) dst_sel:DWORD dst_unused:UNUSED_PAD src0_sel:DWORD src1_sel:BYTE_0
	v_lshlrev_b32_e32 v5, 1, v4
	v_lshrrev_b32_e32 v7, 2, v4
	s_add_u32 s36, s18, s36
	v_and_b32_e32 v3, 32, v3
	v_bfe_i32 v2, v2, 0, 16
	v_and_b32_e32 v5, 24, v5
	v_and_b32_e32 v7, 4, v7
	s_addc_u32 s37, s30, s37
	s_add_i32 s35, s27, 0
	v_or3_b32 v5, v6, v7, v5
	v_add_lshl_u32 v2, v3, v2, 1
	s_add_i32 m0, s35, 0x10000
	v_lshl_add_u32 v72, v5, 8, v2
	global_load_lds_dwordx4 v68, s[36:37]
	s_add_i32 m0, s35, 0x12000
	s_add_i32 s56, s35, 0x2000
	global_load_lds_dwordx4 v72, s[36:37]
	s_mov_b32 m0, s35
	v_lshl_add_u32 v70, v4, 8, v2
	global_load_lds_dwordx4 v66, s[10:11]
	s_mov_b32 m0, s56
	s_add_u32 s40, s36, 0x8000
	global_load_lds_dwordx4 v70, s[10:11]
	s_addc_u32 s41, s37, 0
	s_add_i32 m0, s35, 0x14000
	v_mov_b32_e32 v69, v0
	global_load_lds_dwordx4 v68, s[40:41]
	s_add_i32 m0, s35, 0x16000
	v_mov_b32_e32 v73, v0
	global_load_lds_dwordx4 v72, s[40:41]
	s_add_u32 s40, s14, 0xe4000
	s_addc_u32 s41, s15, 0
	s_add_i32 s57, s35, 0x4000
	s_mov_b32 m0, s57
	s_add_i32 s58, s35, 0x6000
	global_load_lds_dwordx4 v66, s[40:41]
	s_mov_b32 m0, s58
	s_cmp_eq_u32 s42, 1
	global_load_lds_dwordx4 v70, s[40:41]
	v_lshl_add_u64 v[2:3], s[36:37], 0, v[68:69]
	s_cselect_b64 s[40:41], -1, 0
	s_cmp_lg_u32 s42, 1
	v_lshl_add_u64 v[4:5], s[36:37], 0, v[72:73]
	s_cbranch_scc1 .LBB0_511
	s_barrier
.LBB0_511:
	s_lshl_b32 s46, s42, 13
	s_lshl_b32 s42, s48, 12
	s_add_i32 m0, s35, 0x18000
	v_lshl_add_u64 v[2:3], v[2:3], 0, s[24:25]
	s_and_b32 s47, s42, 0x3000
	s_waitcnt vmcnt(4)
	s_barrier
	global_load_lds_dwordx4 v[2:3], off
	s_add_i32 m0, s35, 0x1a000
	s_add_u32 s42, s14, 0xdc080
	v_mov_b32_e32 v67, v0
	v_lshl_add_u64 v[2:3], v[4:5], 0, s[24:25]
	s_addc_u32 s43, s15, 0
	s_add_i32 s59, s35, 0x8000
	v_mov_b32_e32 v71, v0
	global_load_lds_dwordx4 v[2:3], off
	v_lshl_add_u64 v[2:3], s[42:43], 0, v[66:67]
	s_mov_b32 m0, s59
	s_add_i32 s60, s35, 0xa000
	global_load_lds_dwordx4 v[2:3], off
	v_lshl_add_u64 v[2:3], s[42:43], 0, v[70:71]
	s_add_u32 s42, s36, 0x8080
	s_mov_b32 m0, s60
	s_addc_u32 s43, s37, 0
	global_load_lds_dwordx4 v[2:3], off
	s_add_i32 m0, s35, 0x1c000
	v_lshl_add_u64 v[2:3], s[42:43], 0, v[68:69]
	global_load_lds_dwordx4 v[2:3], off
	v_lshl_add_u64 v[2:3], s[42:43], 0, v[72:73]
	s_add_i32 m0, s35, 0x1e000
	s_cmpk_lt_u32 s6, 0x100
	global_load_lds_dwordx4 v[2:3], off
	v_lshrrev_b32_e32 v2, 1, v1
	v_and_b32_e32 v2, 24, v2
	v_lshlrev_b32_e32 v3, 6, v1
	v_and_b32_e32 v74, 0x3c0, v3
	v_lshlrev_b32_e32 v3, 1, v2
	v_lshlrev_b32_e32 v1, 2, v1
	v_or_b32_e32 v4, v3, v74
	v_and_b32_e32 v1, 32, v1
	v_bitop3_b32 v3, v3, v1, v74 bitop3:0x36
	v_bitop3_b32 v4, v4, s46, v1 bitop3:0xde
	s_waitcnt vmcnt(6)
	s_cselect_b64 s[42:43], -1, 0
	s_add_u32 s46, s14, 0x1ce10000
	v_or_b32_e32 v1, s47, v3
	s_addc_u32 s47, s15, 0
	s_lshl_b32 s6, s62, 2
	v_readlane_b32 s14, v255, 38
	v_mov_b32_e32 v75, v0
	v_or_b32_e32 v76, 0x400, v74
	v_mov_b32_e32 v77, v0
	v_or_b32_e32 v78, 0x800, v74
	v_mov_b32_e32 v79, v0
	v_or_b32_e32 v80, 0xc00, v74
	v_mov_b32_e32 v81, v0
	v_lshl_or_b32 v84, s48, 5, v2
	s_add_i32 s61, s14, s6
	s_addk_i32 s61, 0x400
	s_mov_b32 s63, 0
	v_add_u32_e32 v85, 0, v4
	s_mov_b64 s[14:15], s[10:11]
	s_barrier
	s_branch .LBB0_514

.LBB0_804:
	s_and_saveexec_b64 s[14:15], s[40:41]
	s_cbranch_execz .LBB0_816
	v_mov_b32_e32 v65, v172
	s_and_b64 vcc, exec, s[84:85]
	s_cbranch_vccz .Lmg_rev
	s_nop 1
	v_add_f32_dpp v65, v65, v65 row_shr:1 row_mask:0xf bank_mask:0xf
	s_nop 1
	v_add_f32_dpp v65, v65, v65 row_shr:2 row_mask:0xf bank_mask:0xf
	s_nop 1
	v_add_f32_dpp v65, v65, v65 row_shr:4 row_mask:0xf bank_mask:0xf
	s_nop 1
	v_add_f32_dpp v65, v65, v65 row_shr:8 row_mask:0xf bank_mask:0xf
	s_nop 1
	v_add_f32_dpp v65, v65, v65 row_bcast:15 row_mask:0xa bank_mask:0xf
	s_nop 1
	v_add_f32_dpp v65, v65, v65 row_bcast:31 row_mask:0xc bank_mask:0xf
	s_nop 1
	v_sub_f32_e32 v66, v171, v65
	v_mov_b32_e32 v68, v66
	s_nop 1
	v_max_f32_dpp v68, v68, v68 row_shr:1 row_mask:0xf bank_mask:0xf
	s_nop 1
	v_max_f32_dpp v68, v68, v68 row_shr:2 row_mask:0xf bank_mask:0xf
	s_nop 1
	v_max_f32_dpp v68, v68, v68 row_shr:4 row_mask:0xf bank_mask:0xf
	s_nop 1
	v_max_f32_dpp v68, v68, v68 row_shr:8 row_mask:0xf bank_mask:0xf
	s_nop 1
	v_max_f32_dpp v68, v68, v68 row_bcast:15 row_mask:0xa bank_mask:0xf
	s_nop 1
	v_max_f32_dpp v68, v68, v68 row_bcast:31 row_mask:0xc bank_mask:0xf
	s_nop 1
	s_mov_b32 s84, 63
	s_branch .Lmg_done
.Lmg_rev:
	s_nop 1
	v_add_f32_dpp v65, v65, v65 row_shl:1 row_mask:0xf bank_mask:0xf
	s_nop 1
	v_add_f32_dpp v65, v65, v65 row_shl:2 row_mask:0xf bank_mask:0xf
	s_nop 1
	v_add_f32_dpp v65, v65, v65 row_shl:4 row_mask:0xf bank_mask:0xf
	s_nop 1
	v_add_f32_dpp v65, v65, v65 row_shl:8 row_mask:0xf bank_mask:0xf
	s_nop 1
	v_readlane_b32 s100, v65, 48
	s_nop 1
	v_mov_b32_e32 v67, s100
	s_nop 1
	v_add_f32_dpp v65, v67, v65 quad_perm:[0,1,2,3] row_mask:0x4 bank_mask:0xf
	s_nop 1
	v_readlane_b32 s100, v65, 32
	s_nop 1
	v_mov_b32_e32 v67, s100
	s_nop 1
	v_add_f32_dpp v65, v67, v65 quad_perm:[0,1,2,3] row_mask:0x2 bank_mask:0xf
	s_nop 1
	v_readlane_b32 s100, v65, 16
	s_nop 1
	v_mov_b32_e32 v67, s100
	s_nop 1
	v_add_f32_dpp v65, v67, v65 quad_perm:[0,1,2,3] row_mask:0x1 bank_mask:0xf
	s_nop 1
	v_sub_f32_e32 v66, v171, v65
	v_mov_b32_e32 v68, v66
	s_nop 1
	v_max_f32_dpp v68, v68, v68 row_shl:1 row_mask:0xf bank_mask:0xf
	s_nop 1
	v_max_f32_dpp v68, v68, v68 row_shl:2 row_mask:0xf bank_mask:0xf
	s_nop 1
	v_max_f32_dpp v68, v68, v68 row_shl:4 row_mask:0xf bank_mask:0xf
	s_nop 1
	v_max_f32_dpp v68, v68, v68 row_shl:8 row_mask:0xf bank_mask:0xf
	s_nop 1
	v_readlane_b32 s100, v68, 48
	s_nop 1
	v_mov_b32_e32 v67, s100
	s_nop 1
	v_max_f32_dpp v68, v67, v68 quad_perm:[0,1,2,3] row_mask:0x4 bank_mask:0xf
	s_nop 1
	v_readlane_b32 s100, v68, 32
	s_nop 1
	v_mov_b32_e32 v67, s100
	s_nop 1
	v_max_f32_dpp v68, v67, v68 quad_perm:[0,1,2,3] row_mask:0x2 bank_mask:0xf
	s_nop 1
	v_readlane_b32 s100, v68, 16
	s_nop 1
	v_mov_b32_e32 v67, s100
	s_nop 1
	v_max_f32_dpp v68, v67, v68 quad_perm:[0,1,2,3] row_mask:0x1 bank_mask:0xf
	s_nop 1
	s_mov_b32 s84, 0
.Lmg_done:
	s_mov_b32 s90, 0x800000
	s_mov_b32 s91, 0xe010000
	s_mov_b32 s92, 0xeac00000
	s_mov_b32 s93, 0xece00000
	s_mov_b32 s94, 0xeac01000
	s_mov_b32 s95, 0xece01000
	s_mov_b32 s96, 0x16850000
	s_mov_b32 s97, 0x16860000
.LBB0_813:
	v_readlane_b32 s100, v68, s84
	v_readlane_b32 s101, v65, s84
	v_max_f32_e32 v59, v68, v68
	v_max_f32_e32 v60, v103, v103
	v_max_f32_e32 v59, v59, v60
	v_mov_b32_e32 v58, s100
	v_mov_b32_e32 v1, s101
	v_max_f32_e32 v58, v58, v58
	v_max_f32_e32 v58, v60, v58
	v_sub_f32_e32 v60, v103, v59
	v_mul_f32_e32 v60, 0x3fb8aa3b, v60
	v_add_f32_e32 v61, v65, v59
	v_exp_f32_e32 v60, v60
	v_mul_f32_e32 v61, 0xbfb8aa3b, v61
	v_sub_f32_e32 v62, v66, v58
	v_exp_f32_e32 v61, v61
	v_mul_f32_e32 v62, 0x3fb8aa3b, v62
	v_exp_f32_e32 v62, v62
	ds_write_b32 v108, v66
	ds_write_b32 v109, v59
	ds_write_b32 v110, v60
	ds_write_b32 v111, v61
	ds_write_b32 v112, v62
	s_and_saveexec_b64 s[84:85], s[42:43]
	s_cbranch_execz .LBB0_815
	v_sub_f32_e32 v59, v103, v58
	v_mul_f32_e32 v59, 0x3fb8aa3b, v59
	v_exp_f32_e32 v59, v59
	v_mov_b32_e32 v60, s29
	ds_write_b32 v60, v59

.LBB0_844:
	s_or_b64 exec, exec, s[10:11]
	s_waitcnt vmcnt(0)
	v_mov_b32_e32 v18, v232
	s_waitcnt vmcnt(0) lgkmcnt(0)
	s_barrier
	s_nop 0
	v_ashrrev_i32_e32 v19, 6, v18
	v_cmp_gt_i32_e32 vcc, 64, v19
	s_and_saveexec_b64 s[10:11], vcc
	s_mov_b64 s[36:37], 0x4000
	s_mov_b64 s[40:41], 0x2200000
	s_cbranch_execz .LBB0_847
	s_load_dwordx2 s[14:15], s[44:45], 0x48
	v_readlane_b32 s26, v255, 32
	v_lshlrev_b32_e32 v1, 6, v18
	v_readlane_b32 s27, v255, 33
	v_and_b32_e32 v1, 0xfc0, v1
	s_waitcnt lgkmcnt(0)
	s_add_u32 s14, s14, s26
	s_addc_u32 s15, s15, s27
	global_load_dwordx4 v[2:5], v1, s[14:15]
	global_load_dwordx4 v[6:9], v1, s[14:15] offset:16
	global_load_dwordx4 v[10:13], v1, s[14:15] offset:32
	global_load_dwordx4 v[14:17], v1, s[14:15] offset:48
	v_readlane_b32 s6, v255, 30
	s_sub_i32 s6, s62, s6
	s_lshr_b32 s14, s6, 6
	s_lshl_b32 s6, s6, 6
	s_mul_i32 s15, s14, 0x1100
	s_and_b32 s6, s6, 0xfc0
	v_cmp_lt_i32_e32 vcc, v231, v225
	s_add_i32 s14, s15, s6
	s_and_b32 s6, s62, 63
	v_cndmask_b32_e32 v1, v223, v231, vcc
	v_cmp_lt_i32_e32 vcc, v230, v225
	s_lshl_b32 s6, s6, 6
	s_add_i32 s6, s6, s15
	v_cndmask_b32_e32 v20, v223, v230, vcc
	v_cmp_lt_i32_e32 vcc, v229, v225
	v_lshlrev_b32_e32 v26, 2, v20
	s_load_dwordx2 s[26:27], s[44:45], 0xb0
	v_cndmask_b32_e32 v20, v223, v229, vcc
	v_cmp_lt_i32_e32 vcc, v222, v225
	v_lshlrev_b32_e32 v27, 2, v20
	v_add_u32_e32 v19, s6, v19
	v_cndmask_b32_e32 v20, v223, v222, vcc
	v_lshlrev_b32_e32 v28, 2, v20
	v_add_u32_e32 v20, 0x100, v19
	v_ashrrev_i32_e32 v21, 31, v20
	v_lshlrev_b64 v[20:21], 11, v[20:21]
	v_and_b32_e32 v18, 63, v18
	v_lshl_or_b32 v20, v18, 5, v20
	v_add_u32_e32 v29, 0xf8, v19
	s_waitcnt lgkmcnt(0)
	v_lshl_add_u64 v[18:19], s[26:27], 0, v[20:21]
	s_mov_b64 s[26:27], 0x25610000
	v_lshlrev_b32_e32 v1, 2, v1
	s_addk_i32 s14, 0x138
	v_lshl_add_u64 v[18:19], v[18:19], 0, s[26:27]
	s_mov_b64 s[26:27], 0
